# retention out_unit: both state tiles' loads requested together (one round trip instead of two)
# baseline (speedup 1.0000x reference)
; #define LAS __attribute__((address_space(3)))
; DI float logsig(float x) { return -log1pf(__expf(-x)); }
; DI void out_unit(const Inputs& in, int l, unsigned char* ws, int half, int u, LAS unsigned char* lds, int tid) {
;     asm volatile("" : "+v"(tid));
;     const int L = half ? 2048 : 4096, NC = L / 128, h = u & 3, sn = u >> 2, s = sn / NC, n = sn % NC, row0 = s * L + n * 128, pos0 = n * 128;
;     bf16_t* proj = (bf16_t*)(ws + WS_PROJ); const float* rtc = (const float*)(ws + WS_RTC); const float* rts = (const float*)(ws + WS_RTS);
;     const bf16_t* SS = (const bf16_t*)(ws + WS_KV + 32 * MiB);
;     const float lgf = logsig(in.ret_decay[l * 8 + h]), lgb = logsig(in.ret_decay[l * 8 + 4 + h]);
.LBB0_731:
	s_ashr_i32 s13, s26, 2
	s_abs_i32 s15, s13
	s_mul_hi_u32 s16, s15, s24
	s_mul_i32 s17, s16, s20
	s_sub_i32 s15, s15, s17
	s_and_b32 s27, s26, 3
	s_ashr_i32 s14, s26, 31
	s_add_i32 s17, s16, 1
	s_sub_i32 s28, s15, s20
	s_cmp_ge_u32 s15, s20
	s_cselect_b32 s16, s17, s16
	s_cselect_b32 s15, s28, s15
	s_add_i32 s17, s16, 1
	s_cmp_ge_u32 s15, s20
	s_cselect_b32 s15, s17, s16
	s_xor_b32 s15, s15, s14
	s_sub_i32 s14, s15, s14
	s_mul_i32 s15, s14, s20
	s_sub_i32 s13, s13, s15
	s_lshl_b32 s14, s14, s21
	s_lshl_b32 s13, s13, 7
	s_or_b32 s44, s27, s77
	s_add_i32 s14, s13, s14
	s_lshl_b64 s[16:17], s[44:45], 2
	s_waitcnt lgkmcnt(0)
	s_add_u32 s16, s4, s16
	v_mov_b32_e32 v66, v64
	s_addc_u32 s17, s5, s17
	global_load_dword v0, v177, s[16:17]
	global_load_dword v166, v177, s[16:17] offset:16
	v_ashrrev_i32_e32 v19, 6, v66
	s_movk_i32 s15, 0x1100
	v_lshlrev_b32_e32 v91, 3, v66
	v_and_b32_e32 v20, 56, v91
	v_lshlrev_b32_e32 v176, 1, v20
	v_or_b32_e32 v21, 64, v91
	v_and_b32_e32 v68, 15, v66
	v_and_b32_e32 v18, 63, v66
	v_or_b32_e32 v141, 16, v68
	v_or_b32_e32 v114, 32, v68
	v_or_b32_e32 v95, 48, v18
	v_or_b32_e32 v112, 64, v68
	v_or_b32_e32 v110, 0x50, v68
	v_or_b32_e32 v108, 0x60, v68
	v_or_b32_e32 v100, 0x70, v18
	v_mul_u32_u24_e32 v96, 0x88, v95
	v_mad_u32_u24 v97, v68, s1, v224
	v_mad_u32_u24 v98, v68, s1, v254
	v_mad_u32_u24 v99, v68, s1, v219
	v_mul_u32_u24_e32 v101, 0x88, v100
	s_waitcnt vmcnt(0)
	v_mul_f32_e32 v0, 0xbfb8aa3b, v0
	v_exp_f32_e32 v2, v0
	s_nop 0
	v_add_f32_e32 v3, 1.0, v2
	v_add_f32_e32 v0, -1.0, v3
	v_sub_f32_e32 v1, v0, v3
	v_add_f32_e32 v1, 1.0, v1
	v_sub_f32_e32 v0, v2, v0
	v_add_f32_e32 v4, v0, v1
	v_frexp_mant_f32_e32 v0, v3
	v_cmp_gt_f32_e32 vcc, s31, v0
	v_cvt_f64_f32_e32 v[0:1], v3
	v_frexp_exp_i32_f64_e32 v0, v[0:1]
	v_subbrev_co_u32_e32 v0, vcc, 0, v0, vcc
	v_sub_u32_e32 v1, 0, v0
	v_ldexp_f32 v3, v3, v1
	v_ldexp_f32 v1, v4, v1
	v_add_f32_e32 v4, -1.0, v3
	v_add_f32_e32 v5, 1.0, v4
	v_sub_f32_e32 v5, v3, v5
	v_add_f32_e32 v5, v1, v5
	v_add_f32_e32 v6, v4, v5
	v_sub_f32_e32 v4, v6, v4
	v_sub_f32_e32 v4, v5, v4
	v_add_f32_e32 v5, 1.0, v3
	v_add_f32_e32 v7, -1.0, v5
	v_sub_f32_e32 v3, v3, v7
	v_add_f32_e32 v1, v1, v3
	v_add_f32_e32 v3, v5, v1
	v_sub_f32_e32 v5, v3, v5
	v_sub_f32_e32 v1, v1, v5
	v_rcp_f32_e32 v5, v3
	v_cvt_f32_i32_e32 v0, v0
	v_cmp_neq_f32_e32 vcc, s34, v2
	v_mul_f32_e32 v7, v6, v5
	v_mul_f32_e32 v8, v3, v7
	v_fma_f32 v9, v7, v3, -v8
	v_fmac_f32_e32 v9, v7, v1
	v_add_f32_e32 v10, v8, v9
	v_sub_f32_e32 v11, v6, v10
	v_sub_f32_e32 v6, v6, v11
	v_sub_f32_e32 v8, v10, v8
	v_sub_f32_e32 v6, v6, v10
	v_add_f32_e32 v4, v4, v6
	v_sub_f32_e32 v6, v8, v9
	v_add_f32_e32 v4, v6, v4
	v_add_f32_e32 v6, v11, v4
	v_mul_f32_e32 v8, v5, v6
	v_mul_f32_e32 v9, v3, v8
	v_fma_f32 v3, v8, v3, -v9
	v_fmac_f32_e32 v3, v8, v1
	v_sub_f32_e32 v1, v11, v6
	v_add_f32_e32 v1, v4, v1
	v_add_f32_e32 v4, v9, v3
	v_sub_f32_e32 v10, v6, v4
	v_sub_f32_e32 v6, v6, v10
	v_sub_f32_e32 v9, v4, v9
	v_sub_f32_e32 v4, v6, v4
	v_add_f32_e32 v1, v1, v4
	v_sub_f32_e32 v3, v9, v3
	v_add_f32_e32 v1, v3, v1
	v_add_f32_e32 v3, v7, v8
	v_add_f32_e32 v1, v10, v1
	v_sub_f32_e32 v4, v3, v7
	v_mul_f32_e32 v1, v5, v1
	v_sub_f32_e32 v4, v8, v4
	v_add_f32_e32 v1, v4, v1
	v_mul_f32_e32 v7, 0x3f317218, v0
	v_add_f32_e32 v4, v3, v1
	v_fma_f32 v8, v0, s33, -v7
	v_mul_f32_e32 v5, v4, v4
	v_fmac_f32_e32 v8, 0xb102e308, v0
	v_sub_f32_e32 v0, v4, v3
	v_fmamk_f32 v6, v5, 0x3e9b6dac, v218
	v_sub_f32_e32 v0, v1, v0
	v_add_f32_e32 v1, v7, v8
	v_fmaak_f32 v6, v5, v6, 0x3f2aaada
	v_sub_f32_e32 v3, v1, v7
	v_ldexp_f32 v7, v4, 1
	v_mul_f32_e32 v4, v4, v5
	v_mul_f32_e32 v4, v4, v6
	v_add_f32_e32 v5, v7, v4
	v_sub_f32_e32 v6, v5, v7
	v_ldexp_f32 v0, v0, 1
	v_sub_f32_e32 v4, v4, v6
	v_add_f32_e32 v0, v0, v4
	v_add_f32_e32 v4, v5, v0
	v_sub_f32_e32 v5, v4, v5
	v_sub_f32_e32 v0, v0, v5
	v_add_f32_e32 v5, v1, v4
	v_sub_f32_e32 v6, v5, v1
	v_sub_f32_e32 v7, v5, v6
	v_sub_f32_e32 v3, v8, v3
	v_sub_f32_e32 v1, v1, v7
	v_sub_f32_e32 v4, v4, v6
	v_add_f32_e32 v1, v4, v1
	v_add_f32_e32 v4, v3, v0
	v_sub_f32_e32 v6, v4, v3
	v_sub_f32_e32 v7, v4, v6
	v_sub_f32_e32 v3, v3, v7
	v_sub_f32_e32 v0, v0, v6
	v_add_f32_e32 v1, v4, v1
	v_add_f32_e32 v0, v0, v3
	v_add_f32_e32 v3, v5, v1
	v_sub_f32_e32 v4, v3, v5
	v_sub_f32_e32 v1, v1, v4
	v_add_f32_e32 v0, v0, v1
	v_add_f32_e32 v0, v3, v0
	v_cndmask_b32_e32 v0, v221, v0, vcc
	v_cmp_ngt_f32_e32 vcc, -1.0, v2
	s_nop 1
	v_cndmask_b32_e32 v0, v222, v0, vcc
	v_cmp_neq_f32_e32 vcc, -1.0, v2
	s_nop 1
	v_cndmask_b32_e32 v0, v223, v0, vcc
	v_cmp_lt_f32_e64 vcc, |v2|, s35
	s_nop 1
	v_cndmask_b32_e32 v60, v0, v2, vcc
	v_mov_b32_e32 v0, v166
	s_waitcnt vmcnt(0)
; DI void out_unit(const Inputs& in, int l, unsigned char* ws, int half, int u, LAS unsigned char* lds, int tid) {
;     ...
;     stage_rot_rm_b(Qt, proj + (size_t)row0 * PC + C_RQ + 128 * h, rtc, rts, pos0, 1.0f, tid);
;     stage_rot_rm_b(Kt, proj + (size_t)row0 * PC + C_RK + 128 * h, rtc, rts, pos0, 0.088388347648318440f, tid);
	v_mul_f32_e32 v0, 0xbfb8aa3b, v0
	v_exp_f32_e32 v2, v0
	s_nop 0
	v_add_f32_e32 v3, 1.0, v2
	v_add_f32_e32 v0, -1.0, v3
	v_sub_f32_e32 v1, v0, v3
	v_add_f32_e32 v1, 1.0, v1
	v_sub_f32_e32 v0, v2, v0
	v_add_f32_e32 v4, v0, v1
	v_frexp_mant_f32_e32 v0, v3
	v_cmp_gt_f32_e32 vcc, s31, v0
	v_cvt_f64_f32_e32 v[0:1], v3
	v_frexp_exp_i32_f64_e32 v0, v[0:1]
	v_subbrev_co_u32_e32 v0, vcc, 0, v0, vcc
	v_sub_u32_e32 v1, 0, v0
	v_ldexp_f32 v3, v3, v1
	v_ldexp_f32 v1, v4, v1
	v_add_f32_e32 v4, -1.0, v3
	v_add_f32_e32 v5, 1.0, v4
	v_sub_f32_e32 v5, v3, v5
	v_add_f32_e32 v5, v1, v5
	v_add_f32_e32 v6, v4, v5
	v_sub_f32_e32 v4, v6, v4
	v_sub_f32_e32 v4, v5, v4
	v_add_f32_e32 v5, 1.0, v3
	v_add_f32_e32 v7, -1.0, v5
	v_sub_f32_e32 v3, v3, v7
	v_add_f32_e32 v1, v1, v3
	v_add_f32_e32 v3, v5, v1
	v_sub_f32_e32 v5, v3, v5
	v_sub_f32_e32 v1, v1, v5
	v_rcp_f32_e32 v5, v3
	v_cvt_f32_i32_e32 v0, v0
	v_cmp_neq_f32_e32 vcc, s34, v2
	v_mul_f32_e32 v7, v6, v5
	v_mul_f32_e32 v8, v3, v7
	v_fma_f32 v9, v7, v3, -v8
	v_fmac_f32_e32 v9, v7, v1
	v_add_f32_e32 v10, v8, v9
	v_sub_f32_e32 v11, v6, v10
	v_sub_f32_e32 v6, v6, v11
	v_sub_f32_e32 v8, v10, v8
	v_sub_f32_e32 v6, v6, v10
	v_add_f32_e32 v4, v4, v6
	v_sub_f32_e32 v6, v8, v9
	v_add_f32_e32 v4, v6, v4
	v_add_f32_e32 v6, v11, v4
	v_mul_f32_e32 v8, v5, v6
	v_mul_f32_e32 v9, v3, v8
	v_fma_f32 v3, v8, v3, -v9
	v_fmac_f32_e32 v3, v8, v1
	v_sub_f32_e32 v1, v11, v6
	v_add_f32_e32 v1, v4, v1
	v_add_f32_e32 v4, v9, v3
	v_sub_f32_e32 v10, v6, v4
	v_sub_f32_e32 v6, v6, v10
	v_sub_f32_e32 v9, v4, v9
	v_sub_f32_e32 v4, v6, v4
	v_add_f32_e32 v1, v1, v4
	v_sub_f32_e32 v3, v9, v3
	v_add_f32_e32 v1, v3, v1
	v_add_f32_e32 v3, v7, v8
	v_add_f32_e32 v1, v10, v1
	v_sub_f32_e32 v4, v3, v7
	v_mul_f32_e32 v1, v5, v1
	v_sub_f32_e32 v4, v8, v4
	v_add_f32_e32 v1, v4, v1
	v_mul_f32_e32 v7, 0x3f317218, v0
	v_add_f32_e32 v4, v3, v1
	v_fma_f32 v8, v0, s33, -v7
	v_mul_f32_e32 v5, v4, v4
	v_fmac_f32_e32 v8, 0xb102e308, v0
	v_sub_f32_e32 v0, v4, v3
	v_fmamk_f32 v6, v5, 0x3e9b6dac, v218
	v_sub_f32_e32 v0, v1, v0
	v_add_f32_e32 v1, v7, v8
	v_fmaak_f32 v6, v5, v6, 0x3f2aaada
	v_sub_f32_e32 v3, v1, v7
	v_ldexp_f32 v7, v4, 1
	v_mul_f32_e32 v4, v4, v5
	v_mul_f32_e32 v4, v4, v6
	v_add_f32_e32 v5, v7, v4
	v_sub_f32_e32 v6, v5, v7
	v_ldexp_f32 v0, v0, 1
	v_sub_f32_e32 v4, v4, v6
	v_add_f32_e32 v0, v0, v4
	v_add_f32_e32 v4, v5, v0
	v_sub_f32_e32 v5, v4, v5
	v_sub_f32_e32 v0, v0, v5
	v_add_f32_e32 v5, v1, v4
	v_sub_f32_e32 v6, v5, v1
	v_sub_f32_e32 v7, v5, v6
	v_sub_f32_e32 v3, v8, v3
	v_sub_f32_e32 v1, v1, v7
	v_sub_f32_e32 v4, v4, v6
	v_add_f32_e32 v1, v4, v1
	v_add_f32_e32 v4, v3, v0
	v_sub_f32_e32 v6, v4, v3
	v_sub_f32_e32 v7, v4, v6
	v_sub_f32_e32 v3, v3, v7
	v_sub_f32_e32 v0, v0, v6
	v_add_f32_e32 v1, v4, v1
	v_add_f32_e32 v0, v0, v3
	v_add_f32_e32 v3, v5, v1
	v_sub_f32_e32 v4, v3, v5
	v_sub_f32_e32 v1, v1, v4
	v_add_f32_e32 v0, v0, v1
	v_add_f32_e32 v0, v3, v0
	v_cndmask_b32_e32 v0, v221, v0, vcc
	v_cmp_ngt_f32_e32 vcc, -1.0, v2
	v_ashrrev_i32_e32 v10, 3, v66
	v_ashrrev_i32_e32 v11, 31, v10
	v_cndmask_b32_e32 v0, v222, v0, vcc
	v_cmp_neq_f32_e32 vcc, -1.0, v2
	v_add_u32_e32 v12, s13, v10
	v_lshlrev_b64 v[8:9], 14, v[10:11]
	v_cndmask_b32_e32 v0, v223, v0, vcc
	v_cmp_lt_f32_e64 vcc, |v2|, s35
	v_ashrrev_i32_e32 v13, 31, v12
	v_lshlrev_b64 v[14:15], 8, v[12:13]
	v_cndmask_b32_e32 v67, v0, v2, vcc
	v_mul_lo_u32 v0, v19, s15
	s_ashr_i32 s15, s14, 31
	s_lshl_b64 s[16:17], s[14:15], 14
	s_add_u32 s15, s6, s16
	s_addc_u32 s17, s7, s17
	s_lshl_b32 s44, s27, 8
	s_add_u32 s16, s15, s44
	s_addc_u32 s17, s17, 0
	v_add_u32_e32 v65, s42, v0
	v_lshl_add_u64 v[0:1], s[16:17], 0, v[8:9]
	v_lshl_add_u64 v[0:1], v[0:1], 0, v[176:177]
	v_lshl_add_u64 v[16:17], s[8:9], 0, v[14:15]
	v_lshlrev_b32_e32 v12, 2, v20
	v_mov_b32_e32 v13, v177
	v_lshl_add_u64 v[14:15], s[10:11], 0, v[14:15]
	global_load_dwordx4 v[4:7], v[0:1], off offset:3072
	s_nop 0
	global_load_dwordx4 v[0:3], v[0:1], off offset:3200
	v_lshl_add_u64 v[22:23], v[16:17], 0, v[12:13]
	v_lshl_add_u64 v[30:31], v[14:15], 0, v[12:13]
	global_load_dwordx4 v[14:17], v[22:23], off offset:16
	s_nop 0
	global_load_dwordx4 v[22:25], v[22:23], off
	s_nop 0
	global_load_dwordx4 v[26:29], v[30:31], off offset:16
	s_nop 0
	global_load_dwordx4 v[30:33], v[30:31], off
	v_add_u32_e32 v58, 64, v10
	v_ashrrev_i32_e32 v59, 31, v58
	v_add_u32_e32 v42, s13, v58
	v_lshlrev_b64 v[62:63], 14, v[58:59]
	v_ashrrev_i32_e32 v43, 31, v42
	v_lshl_add_u64 v[34:35], s[16:17], 0, v[62:63]
	v_lshlrev_b64 v[42:43], 8, v[42:43]
	v_lshl_add_u64 v[38:39], v[34:35], 0, v[176:177]
	v_lshl_add_u64 v[44:45], s[8:9], 0, v[42:43]
	global_load_dwordx4 v[34:37], v[38:39], off offset:3072
	s_nop 0
	global_load_dwordx4 v[38:41], v[38:39], off offset:3200
	v_lshl_add_u64 v[46:47], v[44:45], 0, v[12:13]
	v_lshl_add_u64 v[42:43], s[10:11], 0, v[42:43]
	v_lshl_add_u64 v[12:13], v[42:43], 0, v[12:13]
	global_load_dwordx4 v[42:45], v[46:47], off offset:16
	s_nop 0
	global_load_dwordx4 v[46:49], v[46:47], off
	s_nop 0
	global_load_dwordx4 v[50:53], v[12:13], off offset:16
	global_load_dwordx4 v[54:57], v[12:13], off
	v_mul_lo_u32 v59, v10, s1
	v_and_b32_e32 v11, 0x78, v10
	v_xad_u32 v11, v11, v20, v59
	v_lshl_add_u32 v61, v11, 1, 0
	s_add_u32 s28, s16, 0x1000
	s_addc_u32 s29, s17, 0
	v_lshl_add_u64 v[168:169], s[28:29], 0, v[8:9]
	v_lshl_add_u64 v[168:169], v[168:169], 0, v[176:177]
	global_load_dwordx4 v[170:173], v[168:169], off
	global_load_dwordx4 v[178:181], v[168:169], off offset:128
	v_lshl_add_u64 v[168:169], s[28:29], 0, v[62:63]
	v_lshl_add_u64 v[168:169], v[168:169], 0, v[176:177]
	global_load_dwordx4 v[182:185], v[168:169], off
	global_load_dwordx4 v[186:189], v[168:169], off offset:128
	s_movk_i32 s13, 0x60
	s_waitcnt vmcnt(15)
; #define LAS __attribute__((address_space(3)))
; DI unsigned cvt_pk_bf16(float lo, float hi) { const f32x2 v = {lo, hi}; return __builtin_bit_cast(unsigned, __builtin_convertvector(v, bf16x2_t)); }
; DI void unpack8(const u32x4 w, float (&f)[8]) { f[0] = bflo(w.x); f[1] = bfhi(w.x); f[2] = bflo(w.y); f[3] = bfhi(w.y); f[4] = bflo(w.z); f[5] = bfhi(w.z); f[6] = bflo(w.w); f[7] = bfhi(w.w); }
; DI void rot_apply(const RotIn& r, float (&o1)[8], float (&o2)[8]) {
;     float x1[8], x2[8]; unpack8(r.a, x1); unpack8(r.b, x2);
; #pragma unroll
;     for (int e = 0; e < 8; ++e) { const float c = e < 4 ? r.ca[e & 3] : r.cb[e & 3], s = e < 4 ? r.sa[e & 3] : r.sb[e & 3]; o1[e] = x1[e] * c - x2[e] * s; o2[e] = x1[e] * s + x2[e] * c; }
; }
; DI void stage_rot_rm_b(LAS unsigned char* dst, const bf16_t* src, const float* rtc, const float* rts, int pos0, float scale, int tid) {
;     const RotIn r0 = rot_load(src, rtc, rts, pos0, tid >> 3, (tid & 7) * 8), r1 = rot_load(src, rtc, rts, pos0, 64 + (tid >> 3), (tid & 7) * 8);
; #pragma unroll
;     for (int k = 0; k < 2; ++k) { const int j = 64 * k + (tid >> 3), d0 = (tid & 7) * 8; float o1[8], o2[8]; rot_apply(k ? r1 : r0, o1, o2);
;         u32x4 w1, w2; w1.x = cvt_pk_bf16(o1[0] * scale, o1[1] * scale); w1.y = cvt_pk_bf16(o1[2] * scale, o1[3] * scale); w1.z = cvt_pk_bf16(o1[4] * scale, o1[5] * scale); w1.w = cvt_pk_bf16(o1[6] * scale, o1[7] * scale);
;         w2.x = cvt_pk_bf16(o2[0] * scale, o2[1] * scale); w2.y = cvt_pk_bf16(o2[2] * scale, o2[3] * scale); w2.z = cvt_pk_bf16(o2[4] * scale, o2[5] * scale); w2.w = cvt_pk_bf16(o2[6] * scale, o2[7] * scale);
;         *(LAS u32x4*)(dst + sw(j, d0) * 2) = w1; *(LAS u32x4*)(dst + sw(j, 64 + d0) * 2) = w2; }
	v_lshlrev_b32_e32 v12, 16, v4
	s_waitcnt vmcnt(14)
	v_lshlrev_b32_e32 v70, 16, v0
	v_and_b32_e32 v71, 0xffff0000, v0
	v_and_b32_e32 v13, 0xffff0000, v4
	s_waitcnt vmcnt(10)
	v_pk_mul_f32 v[72:73], v[30:31], v[70:71]
	v_lshlrev_b32_e32 v0, 16, v1
	v_pk_fma_f32 v[72:73], v[22:23], v[12:13], v[72:73] neg_lo:[0,0,1] neg_hi:[0,0,1]
	v_pk_mul_f32 v[12:13], v[30:31], v[12:13]
	v_and_b32_e32 v1, 0xffff0000, v1
	v_pk_fma_f32 v[12:13], v[22:23], v[70:71], v[12:13]
	v_lshlrev_b32_e32 v4, 16, v5
	v_and_b32_e32 v5, 0xffff0000, v5
	v_pk_mul_f32 v[70:71], v[32:33], v[0:1]
	s_nop 0
	v_pk_fma_f32 v[70:71], v[24:25], v[4:5], v[70:71] neg_lo:[0,0,1] neg_hi:[0,0,1]
	v_pk_mul_f32 v[4:5], v[32:33], v[4:5]
	s_nop 0
	v_pk_fma_f32 v[74:75], v[24:25], v[0:1], v[4:5]
	v_lshlrev_b32_e32 v4, 16, v2
	v_and_b32_e32 v5, 0xffff0000, v2
	v_lshlrev_b32_e32 v0, 16, v6
	v_and_b32_e32 v1, 0xffff0000, v6
	v_pk_mul_f32 v[76:77], v[26:27], v[4:5]
	v_lshlrev_b32_e32 v2, 16, v3
	v_pk_fma_f32 v[76:77], v[14:15], v[0:1], v[76:77] neg_lo:[0,0,1] neg_hi:[0,0,1]
	v_pk_mul_f32 v[0:1], v[26:27], v[0:1]
	v_and_b32_e32 v3, 0xffff0000, v3
	v_pk_fma_f32 v[78:79], v[14:15], v[4:5], v[0:1]
	v_lshlrev_b32_e32 v0, 16, v7
	v_and_b32_e32 v1, 0xffff0000, v7
	v_pk_mul_f32 v[4:5], v[28:29], v[2:3]
	v_cvt_pk_bf16_f32 v6, v78, v79
	v_pk_fma_f32 v[4:5], v[16:17], v[0:1], v[4:5] neg_lo:[0,0,1] neg_hi:[0,0,1]
	v_pk_mul_f32 v[0:1], v[28:29], v[0:1]
	s_nop 0
	v_pk_fma_f32 v[80:81], v[16:17], v[2:3], v[0:1]
	v_cvt_pk_bf16_f32 v0, v72, v73
	v_cvt_pk_bf16_f32 v1, v70, v71
	v_cvt_pk_bf16_f32 v2, v76, v77
	v_cvt_pk_bf16_f32 v3, v4, v5
	ds_write_b128 v61, v[0:3]
	v_bitop3_b32 v0, v21, s0, v10 bitop3:0x48
	v_add_u32_e32 v0, v0, v59
	v_cvt_pk_bf16_f32 v4, v12, v13
	v_cvt_pk_bf16_f32 v5, v74, v75
	v_cvt_pk_bf16_f32 v7, v80, v81
	v_lshl_add_u32 v69, v0, 1, 0
	s_waitcnt vmcnt(8)
	v_lshlrev_b32_e32 v2, 16, v38
	v_and_b32_e32 v3, 0xffff0000, v38
	ds_write_b128 v69, v[4:7]
	v_lshlrev_b32_e32 v0, 16, v34
	v_and_b32_e32 v1, 0xffff0000, v34
	s_waitcnt vmcnt(4)
	v_pk_mul_f32 v[4:5], v[54:55], v[2:3]
	s_nop 0
	v_pk_fma_f32 v[4:5], v[46:47], v[0:1], v[4:5] neg_lo:[0,0,1] neg_hi:[0,0,1]
	v_pk_mul_f32 v[0:1], v[54:55], v[0:1]
	s_nop 0
	v_pk_fma_f32 v[6:7], v[46:47], v[2:3], v[0:1]
	v_lshlrev_b32_e32 v2, 16, v39
	v_and_b32_e32 v3, 0xffff0000, v39
	v_lshlrev_b32_e32 v0, 16, v35
	v_and_b32_e32 v1, 0xffff0000, v35
	v_pk_mul_f32 v[10:11], v[56:57], v[2:3]
	s_nop 0
	v_pk_fma_f32 v[10:11], v[48:49], v[0:1], v[10:11] neg_lo:[0,0,1] neg_hi:[0,0,1]
	v_pk_mul_f32 v[0:1], v[56:57], v[0:1]
	s_nop 0
	v_pk_fma_f32 v[12:13], v[48:49], v[2:3], v[0:1]
	v_lshlrev_b32_e32 v2, 16, v40
	v_and_b32_e32 v3, 0xffff0000, v40
	v_lshlrev_b32_e32 v0, 16, v36
	v_and_b32_e32 v1, 0xffff0000, v36
	v_pk_mul_f32 v[34:35], v[50:51], v[2:3]
	s_nop 0
	v_pk_fma_f32 v[34:35], v[42:43], v[0:1], v[34:35] neg_lo:[0,0,1] neg_hi:[0,0,1]
	v_pk_mul_f32 v[0:1], v[50:51], v[0:1]
	s_nop 0
	v_pk_fma_f32 v[38:39], v[42:43], v[2:3], v[0:1]
	v_lshlrev_b32_e32 v2, 16, v41
	v_and_b32_e32 v3, 0xffff0000, v41
	v_lshlrev_b32_e32 v0, 16, v37
	v_and_b32_e32 v1, 0xffff0000, v37
	v_pk_mul_f32 v[36:37], v[52:53], v[2:3]
	s_nop 0
	v_pk_fma_f32 v[36:37], v[44:45], v[0:1], v[36:37] neg_lo:[0,0,1] neg_hi:[0,0,1]
	v_pk_mul_f32 v[0:1], v[52:53], v[0:1]
	s_nop 0
	v_pk_fma_f32 v[40:41], v[44:45], v[2:3], v[0:1]
	v_cvt_pk_bf16_f32 v1, v10, v11
	v_add_u32_e32 v10, 0x2200, v59
	v_and_b32_e32 v11, 0x78, v58
	v_xad_u32 v11, v11, v20, v10
	v_cvt_pk_bf16_f32 v0, v4, v5
	v_cvt_pk_bf16_f32 v2, v34, v35
	v_cvt_pk_bf16_f32 v3, v36, v37
	v_cvt_pk_bf16_f32 v4, v6, v7
	v_cvt_pk_bf16_f32 v7, v40, v41
	v_lshl_add_u32 v40, v11, 1, 0
	ds_write_b128 v40, v[0:3]
	v_bitop3_b32 v0, v58, s0, v21 bitop3:0x48
	v_add_u32_e32 v0, v0, v10
	v_cvt_pk_bf16_f32 v5, v12, v13
	v_cvt_pk_bf16_f32 v6, v38, v39
	v_lshl_add_u32 v41, v0, 1, 0
	ds_write_b128 v41, v[4:7]
	s_nop 0
	v_ashrrev_i32_e32 v58, 4, v66
	v_ashrrev_i32_e32 v59, 31, v58
	v_bitop3_b32 v134, v58, s0, v91 bitop3:0x48
	s_waitcnt vmcnt(3)
	v_mov_b32_e32 v0, v170
	v_mov_b32_e32 v1, v171
	v_mov_b32_e32 v2, v172
	v_mov_b32_e32 v3, v173
	v_lshlrev_b32_e32 v12, 16, v0
	s_waitcnt vmcnt(2)
	v_mov_b32_e32 v4, v178
	v_mov_b32_e32 v5, v179
	v_mov_b32_e32 v6, v180
	v_mov_b32_e32 v7, v181
	v_lshlrev_b32_e32 v20, 16, v4
	v_and_b32_e32 v21, 0xffff0000, v4
	v_and_b32_e32 v13, 0xffff0000, v0
	v_pk_mul_f32 v[38:39], v[22:23], v[20:21]
	v_pk_mul_f32 v[20:21], v[30:31], v[20:21]
	v_pk_fma_f32 v[38:39], v[30:31], v[12:13], v[38:39]
	v_pk_fma_f32 v[12:13], v[22:23], v[12:13], v[20:21] neg_lo:[0,0,1] neg_hi:[0,0,1]
	v_lshlrev_b32_e32 v20, 16, v5
	v_pk_mul_f32 v[12:13], v[12:13], s[76:77] op_sel_hi:[1,0]
	v_and_b32_e32 v21, 0xffff0000, v5
	v_cvt_pk_bf16_f32 v0, v12, v13
	v_pk_mul_f32 v[12:13], v[38:39], s[76:77] op_sel_hi:[1,0]
	v_pk_mul_f32 v[22:23], v[24:25], v[20:21]
	v_cvt_pk_bf16_f32 v4, v12, v13
	v_lshlrev_b32_e32 v12, 16, v1
	v_and_b32_e32 v13, 0xffff0000, v1
	v_pk_mul_f32 v[20:21], v[32:33], v[20:21]
	v_pk_fma_f32 v[22:23], v[32:33], v[12:13], v[22:23]
	v_pk_fma_f32 v[12:13], v[24:25], v[12:13], v[20:21] neg_lo:[0,0,1] neg_hi:[0,0,1]
	v_lshlrev_b32_e32 v20, 16, v6
	v_pk_mul_f32 v[12:13], v[12:13], s[76:77] op_sel_hi:[1,0]
	v_and_b32_e32 v21, 0xffff0000, v6
	v_cvt_pk_bf16_f32 v1, v12, v13
	v_pk_mul_f32 v[12:13], v[22:23], s[76:77] op_sel_hi:[1,0]
	v_pk_mul_f32 v[22:23], v[14:15], v[20:21]
	v_cvt_pk_bf16_f32 v5, v12, v13
	v_lshlrev_b32_e32 v12, 16, v2
	v_and_b32_e32 v13, 0xffff0000, v2
	v_pk_mul_f32 v[20:21], v[26:27], v[20:21]
	v_pk_fma_f32 v[22:23], v[26:27], v[12:13], v[22:23]
	v_pk_fma_f32 v[12:13], v[14:15], v[12:13], v[20:21] neg_lo:[0,0,1] neg_hi:[0,0,1]
	v_lshlrev_b32_e32 v14, 16, v7
	v_pk_mul_f32 v[12:13], v[12:13], s[76:77] op_sel_hi:[1,0]
	v_and_b32_e32 v15, 0xffff0000, v7
	v_cvt_pk_bf16_f32 v2, v12, v13
	v_pk_mul_f32 v[12:13], v[22:23], s[76:77] op_sel_hi:[1,0]
	v_pk_mul_f32 v[20:21], v[16:17], v[14:15]
	v_cvt_pk_bf16_f32 v6, v12, v13
	v_lshlrev_b32_e32 v12, 16, v3
	v_and_b32_e32 v13, 0xffff0000, v3
	v_pk_mul_f32 v[14:15], v[28:29], v[14:15]
	v_pk_fma_f32 v[20:21], v[28:29], v[12:13], v[20:21]
	v_pk_fma_f32 v[12:13], v[16:17], v[12:13], v[14:15] neg_lo:[0,0,1] neg_hi:[0,0,1]
	v_mul_u32_u24_e32 v17, 0x88, v68
	v_pk_mul_f32 v[12:13], v[12:13], s[76:77] op_sel_hi:[1,0]
	s_nop 0
	v_cvt_pk_bf16_f32 v3, v12, v13
	v_pk_mul_f32 v[12:13], v[20:21], s[76:77] op_sel_hi:[1,0]
	v_mad_u32_u24 v20, v68, s1, v225
	v_cvt_pk_bf16_f32 v7, v12, v13
	ds_write_b128 v61, v[0:3] offset:34816
	ds_write_b128 v69, v[4:7] offset:34816
	s_waitcnt vmcnt(0)
; #define LAS __attribute__((address_space(3)))
; DI void stage_rot_rm_b(LAS unsigned char* dst, const bf16_t* src, const float* rtc, const float* rts, int pos0, float scale, int tid) {
;     ...
;     for (int k = 0; k < 2; ++k) { const int j = 64 * k + (tid >> 3), d0 = (tid & 7) * 8; float o1[8], o2[8]; rot_apply(k ? r1 : r0, o1, o2);
;         u32x4 w1, w2; w1.x = cvt_pk_bf16(o1[0] * scale, o1[1] * scale); w1.y = cvt_pk_bf16(o1[2] * scale, o1[3] * scale); w1.z = cvt_pk_bf16(o1[4] * scale, o1[5] * scale); w1.w = cvt_pk_bf16(o1[6] * scale, o1[7] * scale);
;         w2.x = cvt_pk_bf16(o2[0] * scale, o2[1] * scale); w2.y = cvt_pk_bf16(o2[2] * scale, o2[3] * scale); w2.z = cvt_pk_bf16(o2[4] * scale, o2[5] * scale); w2.w = cvt_pk_bf16(o2[6] * scale, o2[7] * scale);
;         *(LAS u32x4*)(dst + sw(j, d0) * 2) = w1; *(LAS u32x4*)(dst + sw(j, 64 + d0) * 2) = w2; }
; }
; DI void stage_rot_T2_b(LAS unsigned char* dF, LAS unsigned char* dB, const bf16_t* src, const float* rtc, const float* rts, int pos0, float scale, float lgf, float lgb, int tid) {
;     LAS bf16_t* F = (LAS bf16_t*)dF; LAS bf16_t* B = (LAS bf16_t*)dB;
;     const RotIn r0 = rot_load(src, rtc, rts, pos0, tid >> 3, (tid & 7) * 8), r1 = rot_load(src, rtc, rts, pos0, 64 + (tid >> 3), (tid & 7) * 8);
; #pragma unroll
;     for (int k = 0; k < 2; ++k) { const int j = 64 * k + (tid >> 3), d0 = (tid & 7) * 8; float o1[8], o2[8]; rot_apply(k ? r1 : r0, o1, o2);
;         const float wf = __expf((float)(127 - j) * lgf) * scale, wb = __expf((float)j * lgb) * scale;
; #pragma unroll
;         for (int e = 0; e < 8; ++e) { const int i1 = sw(d0 + e, j), i2 = sw(64 + d0 + e, j); F[i1] = f2bf(o1[e] * wf); F[i2] = f2bf(o2[e] * wf); B[i1] = f2bf(o1[e] * wb); B[i2] = f2bf(o2[e] * wb); } }
; }
; DI void stage_T(LAS unsigned char* dst, const bf16_t* src, int tid) {
;     LAS bf16_t* T = (LAS bf16_t*)dst;
;     for (int it = tid; it < 2048; it += 512) { const int j = it >> 4, c0 = (it & 15) * 8; const u32x4 w = *(const u32x4*)(src + (size_t)j * PC + c0);
;         T[sw(c0 + 0, j)] = (bf16_t)(w.x & 0xffff); T[sw(c0 + 1, j)] = (bf16_t)(w.x >> 16); T[sw(c0 + 2, j)] = (bf16_t)(w.y & 0xffff); T[sw(c0 + 3, j)] = (bf16_t)(w.y >> 16);
;         T[sw(c0 + 4, j)] = (bf16_t)(w.z & 0xffff); T[sw(c0 + 5, j)] = (bf16_t)(w.z >> 16); T[sw(c0 + 6, j)] = (bf16_t)(w.w & 0xffff); T[sw(c0 + 7, j)] = (bf16_t)(w.w >> 16); }
; }
	v_mov_b32_e32 v8, v182
	v_mov_b32_e32 v9, v183
	v_mov_b32_e32 v10, v184
	v_mov_b32_e32 v11, v185
	v_mov_b32_e32 v34, v186
	v_mov_b32_e32 v35, v187
	v_mov_b32_e32 v36, v188
	v_mov_b32_e32 v37, v189
	v_lshlrev_b32_e32 v2, 16, v34
	v_and_b32_e32 v3, 0xffff0000, v34
	v_lshlrev_b32_e32 v0, 16, v8
	v_and_b32_e32 v1, 0xffff0000, v8
	v_pk_mul_f32 v[4:5], v[46:47], v[2:3]
	v_pk_mul_f32 v[2:3], v[54:55], v[2:3]
	v_pk_fma_f32 v[4:5], v[54:55], v[0:1], v[4:5]
	v_pk_fma_f32 v[0:1], v[46:47], v[0:1], v[2:3] neg_lo:[0,0,1] neg_hi:[0,0,1]
	v_pk_mul_f32 v[2:3], v[4:5], s[76:77] op_sel_hi:[1,0]
	v_lshlrev_b32_e32 v6, 16, v35
	v_and_b32_e32 v7, 0xffff0000, v35
	v_cvt_pk_bf16_f32 v4, v2, v3
	v_lshlrev_b32_e32 v2, 16, v9
	v_and_b32_e32 v3, 0xffff0000, v9
	v_pk_mul_f32 v[8:9], v[48:49], v[6:7]
	v_pk_mul_f32 v[6:7], v[56:57], v[6:7]
	v_pk_fma_f32 v[8:9], v[56:57], v[2:3], v[8:9]
	v_pk_fma_f32 v[2:3], v[48:49], v[2:3], v[6:7] neg_lo:[0,0,1] neg_hi:[0,0,1]
	v_pk_mul_f32 v[0:1], v[0:1], s[76:77] op_sel_hi:[1,0]
	v_pk_mul_f32 v[2:3], v[2:3], s[76:77] op_sel_hi:[1,0]
	v_cvt_pk_bf16_f32 v0, v0, v1
	v_cvt_pk_bf16_f32 v1, v2, v3
	v_pk_mul_f32 v[2:3], v[8:9], s[76:77] op_sel_hi:[1,0]
	v_lshlrev_b32_e32 v6, 16, v36
	v_and_b32_e32 v7, 0xffff0000, v36
	v_cvt_pk_bf16_f32 v5, v2, v3
	v_lshlrev_b32_e32 v2, 16, v10
	v_and_b32_e32 v3, 0xffff0000, v10
	v_pk_mul_f32 v[8:9], v[42:43], v[6:7]
	v_pk_mul_f32 v[6:7], v[50:51], v[6:7]
	v_pk_fma_f32 v[8:9], v[50:51], v[2:3], v[8:9]
	v_pk_fma_f32 v[2:3], v[42:43], v[2:3], v[6:7] neg_lo:[0,0,1] neg_hi:[0,0,1]
	v_pk_mul_f32 v[6:7], v[8:9], s[76:77] op_sel_hi:[1,0]
	v_lshlrev_b32_e32 v8, 16, v11
	v_and_b32_e32 v9, 0xffff0000, v11
	v_lshlrev_b32_e32 v10, 16, v37
	v_and_b32_e32 v11, 0xffff0000, v37
	v_pk_mul_f32 v[12:13], v[44:45], v[10:11]
	v_pk_mul_f32 v[10:11], v[52:53], v[10:11]
	v_pk_fma_f32 v[12:13], v[52:53], v[8:9], v[12:13]
	v_pk_fma_f32 v[8:9], v[44:45], v[8:9], v[10:11] neg_lo:[0,0,1] neg_hi:[0,0,1]
	v_pk_mul_f32 v[2:3], v[2:3], s[76:77] op_sel_hi:[1,0]
	v_pk_mul_f32 v[8:9], v[8:9], s[76:77] op_sel_hi:[1,0]
	v_cvt_pk_bf16_f32 v2, v2, v3
	v_cvt_pk_bf16_f32 v3, v8, v9
	v_pk_mul_f32 v[8:9], v[12:13], s[76:77] op_sel_hi:[1,0]
	v_cvt_pk_bf16_f32 v6, v6, v7
	v_cvt_pk_bf16_f32 v7, v8, v9
	v_and_b32_e32 v8, 0x78, v91
	v_lshlrev_b32_e32 v176, 1, v8
	ds_write_b128 v40, v[0:3] offset:34816
	ds_write_b128 v41, v[4:7] offset:34816
	v_lshl_add_u64 v[0:1], s[16:17], 0, v[176:177]
	v_lshl_add_u64 v[4:5], v[0:1], 0, s[36:37]
	v_lshlrev_b64 v[0:1], 14, v[58:59]
	v_lshl_add_u64 v[6:7], v[4:5], 0, v[0:1]
	v_add_u32_e32 v0, 0x200, v66
	v_ashrrev_i32_e32 v56, 4, v0
	v_ashrrev_i32_e32 v57, 31, v56
	v_lshlrev_b64 v[0:1], 14, v[56:57]
	v_lshl_add_u64 v[2:3], v[4:5], 0, v[0:1]
	v_add_u32_e32 v0, 0x400, v66
	v_add_u32_e32 v9, 0x600, v66
	v_ashrrev_i32_e32 v54, 4, v0
	v_ashrrev_i32_e32 v52, 4, v9
	v_ashrrev_i32_e32 v55, 31, v54
	v_ashrrev_i32_e32 v53, 31, v52
	v_lshlrev_b64 v[0:1], 14, v[54:55]
	v_lshlrev_b64 v[10:11], 14, v[52:53]
	v_mov_b32_e32 v9, s82
	v_lshl_add_u64 v[0:1], v[4:5], 0, v[0:1]
	v_lshl_add_u64 v[4:5], v[4:5], 0, v[10:11]
	v_mad_u32_u24 v10, v8, s38, v9
	v_lshlrev_b32_e32 v9, 1, v58
	v_lshlrev_b32_e32 v8, 1, v134
	v_and_b32_e32 v9, 14, v9
	v_add3_u32 v11, v10, v8, v9
	global_load_dwordx4 v[150:153], v[6:7], off
	global_load_dwordx4 v[154:157], v[2:3], off
	global_load_dwordx4 v[158:161], v[0:1], off
	global_load_dwordx4 v[162:165], v[4:5], off
	s_waitcnt vmcnt(0)
	v_mov_b32_e32 v6, v150
	v_mov_b32_e32 v7, v151
	v_mov_b32_e32 v8, v152
	v_mov_b32_e32 v9, v153
	ds_write_b16 v11, v6
	ds_write_b16_d16_hi v11, v6 offset:272
	ds_write_b16 v11, v7 offset:544
	ds_write_b16_d16_hi v11, v7 offset:816
	ds_write_b16 v11, v8 offset:1088
	ds_write_b16_d16_hi v11, v8 offset:1360
	ds_write_b16 v11, v9 offset:1632
	ds_write_b16_d16_hi v11, v9 offset:1904
	v_bitop3_b32 v135, v56, s0, v91 bitop3:0x48
	v_lshlrev_b32_e32 v7, 1, v56
	v_lshlrev_b32_e32 v6, 1, v135
	v_and_b32_e32 v7, 14, v7
	v_add3_u32 v11, v10, v6, v7
	s_nop 0
	v_mov_b32_e32 v6, v154
	v_mov_b32_e32 v7, v155
	v_mov_b32_e32 v8, v156
	v_mov_b32_e32 v9, v157
	ds_write_b16 v11, v6
	ds_write_b16_d16_hi v11, v6 offset:272
	ds_write_b16 v11, v7 offset:544
	ds_write_b16_d16_hi v11, v7 offset:816
	ds_write_b16 v11, v8 offset:1088
	ds_write_b16_d16_hi v11, v8 offset:1360
	ds_write_b16 v11, v9 offset:1632
	s_nop 0
	ds_write_b16_d16_hi v11, v9 offset:1904
	v_bitop3_b32 v136, v54, s0, v91 bitop3:0x48
	v_lshlrev_b32_e32 v9, 1, v54
	v_lshlrev_b32_e32 v8, 1, v136
	v_and_b32_e32 v9, 14, v9
	v_add3_u32 v8, v10, v8, v9
	s_nop 0
	v_mov_b32_e32 v0, v158
	v_mov_b32_e32 v1, v159
	v_mov_b32_e32 v2, v160
	v_mov_b32_e32 v3, v161
	ds_write_b16 v8, v0
	ds_write_b16_d16_hi v8, v0 offset:272
	ds_write_b16 v8, v1 offset:544
	ds_write_b16_d16_hi v8, v1 offset:816
	ds_write_b16 v8, v2 offset:1088
	ds_write_b16_d16_hi v8, v2 offset:1360
	ds_write_b16 v8, v3 offset:1632
	ds_write_b16_d16_hi v8, v3 offset:1904
	v_bitop3_b32 v133, v52, s0, v91 bitop3:0x48
	v_lshlrev_b32_e32 v1, 1, v52
	v_lshlrev_b32_e32 v0, 1, v133
	v_and_b32_e32 v1, 14, v1
	v_add3_u32 v0, v10, v0, v1
	v_lshlrev_b32_e32 v69, 4, v19
	s_nop 0
	v_mov_b32_e32 v4, v162
	v_mov_b32_e32 v5, v163
	v_mov_b32_e32 v6, v164
	v_mov_b32_e32 v7, v165
	ds_write_b16 v0, v4
	ds_write_b16_d16_hi v0, v4 offset:272
	ds_write_b16 v0, v5 offset:544
	ds_write_b16_d16_hi v0, v5 offset:816
	ds_write_b16 v0, v6 offset:1088
	ds_write_b16_d16_hi v0, v6 offset:1360
	ds_write_b16 v0, v7 offset:1632
	ds_write_b16_d16_hi v0, v7 offset:1904
	v_or_b32_e32 v0, v69, v68
	v_lshrrev_b32_e32 v8, 1, v66
	v_and_b32_e32 v16, 24, v8
	v_mul_lo_u32 v50, v0, s1
	v_bitop3_b32 v51, v69, s0, v68 bitop3:0xc8
	v_xad_u32 v0, v51, v16, v50
	v_lshl_add_u32 v53, v0, 1, 0
	s_waitcnt lgkmcnt(0)
	s_barrier
; #define LAS __attribute__((address_space(3)))
; DI void mma16(f32x4 (&acc)[8], const LAS unsigned char* At, int arow0, const LAS unsigned char* Bt, int lane) {
;     const int l15 = lane & 15, quad = lane >> 4;
; #pragma unroll
;     for (int ks = 0; ks < 4; ++ks) {
;         const bf16x8 a = *(const LAS bf16x8*)(At + sw(arow0 + l15, 32 * ks + 8 * quad) * 2);
; #pragma unroll
;         for (int cg = 0; cg < 8; ++cg) { const bf16x8 b = *(const LAS bf16x8*)(Bt + sw(16 * cg + l15, 32 * ks + 8 * quad) * 2);
;             acc[cg] = __builtin_amdgcn_mfma_f32_16x16x32_bf16(a, b, acc[cg], 0, 0, 0); }
;     }
; }
	v_and_b32_e32 v19, 8, v66
	ds_read_b128 v[0:3], v53
	v_bitop3_b32 v4, v8, v19, 24 bitop3:0x6c
	v_bitop3_b32 v8, v141, v8, 24 bitop3:0x28
	v_mad_u32_u24 v21, v68, s1, v220
	v_bitop3_b32 v12, v114, v16, 40 bitop3:0x6c
	v_bitop3_b32 v22, v95, v16, 56 bitop3:0x6c
	v_bitop3_b32 v26, v112, v16, s39 bitop3:0x6c
	v_bitop3_b32 v30, v110, v16, s40 bitop3:0x6c
	v_bitop3_b32 v34, v108, v16, s41 bitop3:0x6c
	v_bitop3_b32 v18, v100, v16, s0 bitop3:0x6c
	v_add_lshl_u32 v104, v4, v17, 1
	v_add_lshl_u32 v105, v8, v20, 1
	v_add_lshl_u32 v106, v12, v21, 1
	v_add_lshl_u32 v107, v22, v96, 1
	v_add_lshl_u32 v109, v26, v97, 1
	v_add_lshl_u32 v111, v30, v98, 1
	v_add_lshl_u32 v113, v34, v99, 1
	v_add_lshl_u32 v115, v18, v101, 1
	v_add_u32_e32 v55, 0, v104
	v_add_u32_e32 v57, 0, v105
	v_add_u32_e32 v59, 0, v106
	v_add_u32_e32 v61, 0, v107
	v_add_u32_e32 v62, 0, v109
	v_add_u32_e32 v63, 0, v111
	v_add_u32_e32 v70, 0, v113
	v_add_u32_e32 v71, 0, v115
	ds_read_b128 v[4:7], v55 offset:34816
	ds_read_b128 v[8:11], v57 offset:34816
	ds_read_b128 v[12:15], v59 offset:34816
	ds_read_b128 v[22:25], v61 offset:34816
	ds_read_b128 v[26:29], v62 offset:34816
	ds_read_b128 v[30:33], v63 offset:34816
	ds_read_b128 v[34:37], v70 offset:34816
	ds_read_b128 v[38:41], v71 offset:34816
	v_bitop3_b32 v42, v16, v19, 32 bitop3:0x36
	v_add_lshl_u32 v116, v42, v17, 1
	v_or_b32_e32 v18, 32, v16
	v_add_u32_e32 v73, 0, v116
	s_waitcnt lgkmcnt(7)
	v_mfma_f32_16x16x32_bf16 v[4:7], v[0:3], v[4:7], 0
	ds_read_b128 v[42:45], v73 offset:34816
	v_or_b32_e32 v102, 0x60, v16
	v_mul_lo_u32 v58, v58, s1
	s_waitcnt lgkmcnt(7)
	v_mfma_f32_16x16x32_bf16 v[8:11], v[0:3], v[8:11], 0
	v_add_lshl_u32 v58, v134, v58, 1
	s_waitcnt lgkmcnt(6)
	v_mfma_f32_16x16x32_bf16 v[12:15], v[0:3], v[12:15], 0
	s_waitcnt lgkmcnt(5)
	v_mfma_f32_16x16x32_bf16 v[22:25], v[0:3], v[22:25], 0
	s_waitcnt lgkmcnt(4)
	v_mfma_f32_16x16x32_bf16 v[26:29], v[0:3], v[26:29], 0
	s_waitcnt lgkmcnt(3)
	v_mfma_f32_16x16x32_bf16 v[30:33], v[0:3], v[30:33], 0
	s_waitcnt lgkmcnt(2)
	v_mfma_f32_16x16x32_bf16 v[34:37], v[0:3], v[34:37], 0
	s_waitcnt lgkmcnt(1)
	v_mfma_f32_16x16x32_bf16 v[0:3], v[0:3], v[38:41], 0
	v_xad_u32 v38, v51, v18, v50
	v_lshl_add_u32 v72, v38, 1, 0
	ds_read_b128 v[38:41], v72
	s_waitcnt lgkmcnt(0)
	v_mfma_f32_16x16x32_bf16 v[4:7], v[38:41], v[42:45], v[4:7]
	v_bitop3_b32 v42, v141, v18, 24 bitop3:0x6c
	v_add_lshl_u32 v117, v42, v20, 1
	v_add_u32_e32 v74, 0, v117
	ds_read_b128 v[42:45], v74 offset:34816
	s_waitcnt lgkmcnt(0)
	v_mfma_f32_16x16x32_bf16 v[8:11], v[38:41], v[42:45], v[8:11]
	v_bitop3_b32 v42, v114, v18, 40 bitop3:0x6c
	v_add_lshl_u32 v118, v42, v21, 1
	v_add_u32_e32 v75, 0, v118
	ds_read_b128 v[42:45], v75 offset:34816
	s_waitcnt lgkmcnt(0)
	v_mfma_f32_16x16x32_bf16 v[12:15], v[38:41], v[42:45], v[12:15]
	v_bitop3_b32 v42, v95, v18, 56 bitop3:0x6c
	v_add_lshl_u32 v119, v42, v96, 1
	v_add_u32_e32 v76, 0, v119
	ds_read_b128 v[42:45], v76 offset:34816
	s_waitcnt lgkmcnt(0)
	v_mfma_f32_16x16x32_bf16 v[22:25], v[38:41], v[42:45], v[22:25]
	v_bitop3_b32 v42, v112, v18, s39 bitop3:0x6c
	v_add_lshl_u32 v120, v42, v97, 1
	v_add_u32_e32 v77, 0, v120
	ds_read_b128 v[42:45], v77 offset:34816
	s_waitcnt lgkmcnt(0)
	v_mfma_f32_16x16x32_bf16 v[26:29], v[38:41], v[42:45], v[26:29]
	v_bitop3_b32 v42, v110, v18, s40 bitop3:0x6c
	v_add_lshl_u32 v121, v42, v98, 1
	v_add_u32_e32 v78, 0, v121
	ds_read_b128 v[42:45], v78 offset:34816
	s_waitcnt lgkmcnt(0)
	v_mfma_f32_16x16x32_bf16 v[42:45], v[38:41], v[42:45], v[30:33]
	s_nop 2
	v_bitop3_b32 v30, v108, v18, s41 bitop3:0x6c
	v_add_lshl_u32 v122, v30, v99, 1
	v_add_u32_e32 v79, 0, v122
	ds_read_b128 v[30:33], v79 offset:34816
	v_bitop3_b32 v18, v100, v18, s0 bitop3:0x6c
	v_add_lshl_u32 v123, v18, v101, 1
	v_add_u32_e32 v80, 0, v123
	s_waitcnt lgkmcnt(0)
	v_mfma_f32_16x16x32_bf16 v[46:49], v[38:41], v[30:33], v[34:37]
	ds_read_b128 v[30:33], v80 offset:34816
	v_or_b32_e32 v18, 64, v16
	s_waitcnt lgkmcnt(0)
	v_mfma_f32_16x16x32_bf16 v[142:145], v[38:41], v[30:33], v[0:3]
	s_nop 2
	v_xad_u32 v0, v51, v18, v50
	v_lshl_add_u32 v81, v0, 1, 0
	ds_read_b128 v[146:149], v81
	v_bitop3_b32 v0, v16, v19, 64 bitop3:0x36
	v_add_lshl_u32 v124, v0, v17, 1
	v_add_u32_e32 v82, 0, v124
	ds_read_b128 v[0:3], v82 offset:34816
	s_waitcnt lgkmcnt(0)
	v_mfma_f32_16x16x32_bf16 v[0:3], v[146:149], v[0:3], v[4:7]
	s_nop 2
	v_bitop3_b32 v4, v141, v18, 24 bitop3:0x6c
	v_add_lshl_u32 v125, v4, v20, 1
	v_add_u32_e32 v83, 0, v125
	ds_read_b128 v[4:7], v83 offset:34816
	s_waitcnt lgkmcnt(0)
	v_mfma_f32_16x16x32_bf16 v[4:7], v[146:149], v[4:7], v[8:11]
	s_nop 2
	v_bitop3_b32 v8, v114, v18, 40 bitop3:0x6c
	v_add_lshl_u32 v126, v8, v21, 1
	v_add_u32_e32 v84, 0, v126
	ds_read_b128 v[8:11], v84 offset:34816
	s_waitcnt lgkmcnt(0)
	v_mfma_f32_16x16x32_bf16 v[8:11], v[146:149], v[8:11], v[12:15]
	s_nop 2
	v_bitop3_b32 v12, v95, v18, 56 bitop3:0x6c
	v_add_lshl_u32 v127, v12, v96, 1
	v_add_u32_e32 v85, 0, v127
	ds_read_b128 v[12:15], v85 offset:34816
	s_waitcnt lgkmcnt(0)
	v_mfma_f32_16x16x32_bf16 v[12:15], v[146:149], v[12:15], v[22:25]
	s_nop 2
	v_bitop3_b32 v22, v112, v18, s39 bitop3:0x6c
	v_add_lshl_u32 v128, v22, v97, 1
	v_add_u32_e32 v86, 0, v128
	ds_read_b128 v[22:25], v86 offset:34816
	s_waitcnt lgkmcnt(0)
	v_mfma_f32_16x16x32_bf16 v[32:35], v[146:149], v[22:25], v[26:29]
	v_bitop3_b32 v22, v110, v18, s40 bitop3:0x6c
	v_add_lshl_u32 v129, v22, v98, 1
	v_add_u32_e32 v87, 0, v129
	ds_read_b128 v[22:25], v87 offset:34816
	s_waitcnt lgkmcnt(0)
; #define LAS __attribute__((address_space(3)))
; DI void out_unit(const Inputs& in, int l, unsigned char* ws, int half, int u, LAS unsigned char* lds, int tid) {
;     ...
;     zero8(F); mma16(F, Qt, 16 * wave, Kt, lane);
; #pragma unroll
;     for (int cg = 0; cg < 8; ++cg)
; #pragma unroll
;         for (int r = 0; r < 4; ++r) { const int i = 16 * wave + 4 * quad + r, j = 16 * cg + l15, df = i - j;
;             const float fac = df >= 0 ? __expf((float)df * lgf) : __expf((float)(-df) * lgb);
;             ((LAS bf16_t*)Ps)[sw(4 * quad + r, j)] = f2bf(F[cg][r] * fac); }
	v_mfma_f32_16x16x32_bf16 v[36:39], v[146:149], v[22:25], v[42:45]
	v_bitop3_b32 v22, v108, v18, s41 bitop3:0x6c
	v_add_lshl_u32 v130, v22, v99, 1
	v_add_u32_e32 v88, 0, v130
	ds_read_b128 v[22:25], v88 offset:34816
	v_bitop3_b32 v18, v100, v18, s0 bitop3:0x6c
	v_bitop3_b32 v16, v16, v19, s13 bitop3:0x36
	v_add_lshl_u32 v131, v18, v101, 1
	v_xad_u32 v18, v51, v102, v50
	v_add_lshl_u32 v132, v16, v17, 1
	v_add_u32_e32 v89, 0, v131
	v_lshl_add_u32 v90, v18, 1, 0
	v_add_u32_e32 v92, 0, v132
	ds_read_b128 v[16:19], v92 offset:34816
	s_waitcnt lgkmcnt(1)
	v_mfma_f32_16x16x32_bf16 v[40:43], v[146:149], v[22:25], v[46:49]
	ds_read_b128 v[22:25], v89 offset:34816
	s_ashr_i32 s13, s12, 31
	s_lshl_b64 s[16:17], s[12:13], 15
	ds_read_b128 v[48:51], v90
	s_waitcnt lgkmcnt(0)
	v_mfma_f32_16x16x32_bf16 v[28:31], v[48:51], v[16:19], v[0:3]
	s_nop 2
	v_bitop3_b32 v0, v141, v102, 24 bitop3:0x6c
	v_add_lshl_u32 v137, v0, v20, 1
	v_add_u32_e32 v93, 0, v137
	ds_read_b128 v[0:3], v93 offset:34816
	v_mfma_f32_16x16x32_bf16 v[44:47], v[146:149], v[22:25], v[142:145]
	s_add_u32 s16, s22, s16
	s_addc_u32 s17, s23, s17
	s_waitcnt lgkmcnt(0)
	v_mfma_f32_16x16x32_bf16 v[24:27], v[48:51], v[0:3], v[4:7]
	v_bitop3_b32 v0, v114, v102, 40 bitop3:0x6c
	v_add_lshl_u32 v138, v0, v21, 1
	v_add_u32_e32 v94, 0, v138
	ds_read_b128 v[0:3], v94 offset:34816
	s_waitcnt lgkmcnt(0)
	v_mfma_f32_16x16x32_bf16 v[20:23], v[48:51], v[0:3], v[8:11]
	v_bitop3_b32 v0, v95, v102, 56 bitop3:0x6c
	v_add_lshl_u32 v139, v0, v96, 1
	v_add_u32_e32 v95, 0, v139
	ds_read_b128 v[0:3], v95 offset:34816
	s_waitcnt lgkmcnt(0)
	v_mfma_f32_16x16x32_bf16 v[16:19], v[48:51], v[0:3], v[12:15]
	v_bitop3_b32 v0, v112, v102, s39 bitop3:0x6c
	v_add_lshl_u32 v140, v0, v97, 1
	v_add_u32_e32 v96, 0, v140
	ds_read_b128 v[0:3], v96 offset:34816
	s_waitcnt lgkmcnt(0)
	v_mfma_f32_16x16x32_bf16 v[12:15], v[48:51], v[0:3], v[32:35]
	v_bitop3_b32 v0, v110, v102, s40 bitop3:0x6c
	s_nop 1
	v_add_lshl_u32 v32, v0, v98, 1
	v_add_u32_e32 v97, 0, v32
	ds_read_b128 v[0:3], v97 offset:34816
	s_waitcnt lgkmcnt(0)
	v_mfma_f32_16x16x32_bf16 v[8:11], v[48:51], v[0:3], v[36:39]
	v_bitop3_b32 v0, v108, v102, s41 bitop3:0x6c
	v_add_lshl_u32 v33, v0, v99, 1
	v_add_u32_e32 v98, 0, v33
	ds_read_b128 v[0:3], v98 offset:34816
	v_lshrrev_b32_e32 v37, 2, v66
	s_waitcnt lgkmcnt(0)
	v_mfma_f32_16x16x32_bf16 v[4:7], v[48:51], v[0:3], v[40:43]
	v_bitop3_b32 v0, v100, v102, s0 bitop3:0x6c
	v_and_b32_e32 v36, 12, v37
	v_add_lshl_u32 v34, v0, v101, 1
	v_or_b32_e32 v101, v36, v69
	v_sub_u32_e32 v38, v101, v68
	v_sub_u32_e32 v39, 0, v38
	v_max_i32_e32 v39, v38, v39
	v_cvt_f32_u32_e32 v39, v39
	v_cmp_gt_i32_e32 vcc, 0, v38
	v_add_u32_e32 v99, 0, v34
	ds_read_b128 v[0:3], v99 offset:34816
	v_cndmask_b32_e32 v38, v60, v67, vcc
	v_mul_f32_e32 v38, v38, v39
	v_mul_f32_e32 v38, 0xbfb8aa3b, v38
	v_exp_f32_e32 v38, v38
	v_and_b32_e32 v35, 7, v66
	v_bitop3_b32 v37, v37, 8, v66 bitop3:0x48
	v_lshl_add_u32 v35, v35, 1, v65
	v_lshlrev_b32_e32 v37, 1, v37
	v_mul_f32_e32 v28, v38, v28
	v_mul_u32_u24_e32 v103, 0x110, v36
	s_waitcnt lgkmcnt(0)
	v_mfma_f32_16x16x32_bf16 v[0:3], v[48:51], v[0:3], v[44:47]
	v_cvt_pk_bf16_f32 v28, v28, s0
	v_add3_u32 v37, v35, v37, v103
	v_or_b32_e32 v48, 1, v101
	ds_write_b16 v37, v28
	v_sub_u32_e32 v28, v48, v68
	v_sub_u32_e32 v38, 0, v28
	v_max_i32_e32 v38, v28, v38
	v_cvt_f32_u32_e32 v38, v38
	v_cmp_gt_i32_e32 vcc, 0, v28
	v_or_b32_e32 v102, 2, v101
	v_or_b32_e32 v100, 3, v101
	v_cndmask_b32_e32 v28, v60, v67, vcc
	v_mul_f32_e32 v28, v28, v38
	v_mul_f32_e32 v28, 0xbfb8aa3b, v28
	v_exp_f32_e32 v28, v28
	v_add_u32_e32 v50, s82, v113
	v_add_u32_e32 v49, s82, v115
	v_add_u32_e32 v51, s82, v116
	v_mul_f32_e32 v28, v28, v29
	v_cvt_pk_bf16_f32 v28, v28, s0
	ds_write_b16 v37, v28 offset:272
	v_sub_u32_e32 v28, v102, v68
	v_sub_u32_e32 v29, 0, v28
	v_max_i32_e32 v29, v28, v29
	v_cvt_f32_u32_e32 v29, v29
	v_cmp_gt_i32_e32 vcc, 0, v28
	v_add_u32_e32 v113, s82, v121
	v_add_u32_e32 v115, s82, v122
	v_cndmask_b32_e32 v28, v60, v67, vcc
	v_mul_f32_e32 v28, v28, v29
	v_mul_f32_e32 v28, 0xbfb8aa3b, v28
	v_exp_f32_e32 v28, v28
	v_add_u32_e32 v121, s82, v128
	v_add_u32_e32 v122, s82, v129
	v_add_u32_e32 v128, s82, v139
	v_mul_f32_e32 v28, v28, v30
	v_cvt_pk_bf16_f32 v28, v28, s0
	ds_write_b16 v37, v28 offset:544
	v_sub_u32_e32 v28, v100, v68
	v_sub_u32_e32 v29, 0, v28
	v_max_i32_e32 v29, v28, v29
	v_cvt_f32_u32_e32 v29, v29
	v_cmp_gt_i32_e32 vcc, 0, v28
	v_add_u32_e32 v129, s82, v140
	s_nop 0
	v_cndmask_b32_e32 v28, v60, v67, vcc
	v_mul_f32_e32 v28, v28, v29
	v_sub_u32_e32 v29, v101, v141
	v_sub_u32_e32 v30, 0, v29
	v_max_i32_e32 v30, v29, v30
	v_cvt_f32_u32_e32 v30, v30
	v_mul_f32_e32 v28, 0xbfb8aa3b, v28
	v_cmp_gt_i32_e32 vcc, 0, v29
	v_exp_f32_e32 v28, v28
	s_nop 0
	v_cndmask_b32_e32 v29, v60, v67, vcc
	v_mul_f32_e32 v29, v29, v30
	v_mul_f32_e32 v29, 0xbfb8aa3b, v29
	v_exp_f32_e32 v29, v29
	v_mul_f32_e32 v28, v28, v31
	v_cvt_pk_bf16_f32 v28, v28, s0
	ds_write_b16 v37, v28 offset:816
	v_bitop3_b32 v28, v141, 24, v36 bitop3:0x48
	v_lshlrev_b32_e32 v28, 1, v28
	v_mul_f32_e32 v24, v29, v24
	v_cvt_pk_bf16_f32 v24, v24, s0
	v_add3_u32 v28, v35, v28, v103
	ds_write_b16 v28, v24
	v_sub_u32_e32 v24, v48, v141
	v_sub_u32_e32 v29, 0, v24
	v_max_i32_e32 v29, v24, v29
	v_cvt_f32_u32_e32 v29, v29
	v_cmp_gt_i32_e32 vcc, 0, v24
	s_nop 1
	v_cndmask_b32_e32 v24, v60, v67, vcc
	v_mul_f32_e32 v24, v24, v29
	v_mul_f32_e32 v24, 0xbfb8aa3b, v24
	v_exp_f32_e32 v24, v24
	s_nop 0
	v_mul_f32_e32 v24, v24, v25
	v_cvt_pk_bf16_f32 v24, v24, s0
	ds_write_b16 v28, v24 offset:272
	v_sub_u32_e32 v24, v102, v141
	v_sub_u32_e32 v25, 0, v24
	v_max_i32_e32 v25, v24, v25
; #define LAS __attribute__((address_space(3)))
; DI void out_unit(const Inputs& in, int l, unsigned char* ws, int half, int u, LAS unsigned char* lds, int tid) {
;     ...
;         for (int r = 0; r < 4; ++r) { const int i = 16 * wave + 4 * quad + r, j = 16 * cg + l15, df = i - j;
;             const float fac = df >= 0 ? __expf((float)df * lgf) : __expf((float)(-df) * lgb);
;             ((LAS bf16_t*)Ps)[sw(4 * quad + r, j)] = f2bf(F[cg][r] * fac); }
	v_cvt_f32_u32_e32 v25, v25
	v_cmp_gt_i32_e32 vcc, 0, v24
	s_nop 1
	v_cndmask_b32_e32 v24, v60, v67, vcc
	v_mul_f32_e32 v24, v24, v25
	v_mul_f32_e32 v24, 0xbfb8aa3b, v24
	v_exp_f32_e32 v24, v24
	s_nop 0
	v_mul_f32_e32 v24, v24, v26
	v_cvt_pk_bf16_f32 v24, v24, s0
	ds_write_b16 v28, v24 offset:544
	v_sub_u32_e32 v24, v100, v141
	v_sub_u32_e32 v25, 0, v24
	v_max_i32_e32 v25, v24, v25
	v_cvt_f32_u32_e32 v25, v25
	v_cmp_gt_i32_e32 vcc, 0, v24
	s_nop 1
	v_cndmask_b32_e32 v24, v60, v67, vcc
	v_mul_f32_e32 v24, v24, v25
	v_sub_u32_e32 v25, v101, v114
	v_sub_u32_e32 v26, 0, v25
	v_max_i32_e32 v26, v25, v26
	v_cvt_f32_u32_e32 v26, v26
	v_mul_f32_e32 v24, 0xbfb8aa3b, v24
	v_cmp_gt_i32_e32 vcc, 0, v25
	v_exp_f32_e32 v24, v24
	s_nop 0
	v_cndmask_b32_e32 v25, v60, v67, vcc
	v_mul_f32_e32 v25, v25, v26
	v_mul_f32_e32 v25, 0xbfb8aa3b, v25
	v_exp_f32_e32 v25, v25
	v_mul_f32_e32 v24, v24, v27
	v_cvt_pk_bf16_f32 v24, v24, s0
	ds_write_b16 v28, v24 offset:816
	v_bitop3_b32 v24, v114, 40, v36 bitop3:0x48
	v_lshlrev_b32_e32 v24, 1, v24
	v_mul_f32_e32 v20, v25, v20
	v_cvt_pk_bf16_f32 v20, v20, s0
	v_add3_u32 v24, v35, v24, v103
	ds_write_b16 v24, v20
	v_sub_u32_e32 v20, v48, v114
	v_sub_u32_e32 v25, 0, v20
	v_max_i32_e32 v25, v20, v25
	v_cvt_f32_u32_e32 v25, v25
	v_cmp_gt_i32_e32 vcc, 0, v20
	s_nop 1
	v_cndmask_b32_e32 v20, v60, v67, vcc
	v_mul_f32_e32 v20, v20, v25
	v_mul_f32_e32 v20, 0xbfb8aa3b, v20
	v_exp_f32_e32 v20, v20
	s_nop 0
	v_mul_f32_e32 v20, v20, v21
	v_cvt_pk_bf16_f32 v20, v20, s0
	ds_write_b16 v24, v20 offset:272
	v_sub_u32_e32 v20, v102, v114
	v_sub_u32_e32 v21, 0, v20
	v_max_i32_e32 v21, v20, v21
	v_cvt_f32_u32_e32 v21, v21
	v_cmp_gt_i32_e32 vcc, 0, v20
	s_nop 1
	v_cndmask_b32_e32 v20, v60, v67, vcc
	v_mul_f32_e32 v20, v20, v21
	v_mul_f32_e32 v20, 0xbfb8aa3b, v20
	v_exp_f32_e32 v20, v20
	s_nop 0
	v_mul_f32_e32 v20, v20, v22
	v_cvt_pk_bf16_f32 v20, v20, s0
	ds_write_b16 v24, v20 offset:544
	v_sub_u32_e32 v20, v100, v114
	v_sub_u32_e32 v21, 0, v20
	v_max_i32_e32 v21, v20, v21
	v_cvt_f32_u32_e32 v21, v21
	v_cmp_gt_i32_e32 vcc, 0, v20
	v_add_u32_e32 v114, s82, v104
	s_nop 0
	v_cndmask_b32_e32 v20, v60, v67, vcc
	v_mul_f32_e32 v20, v20, v21
	v_mul_f32_e32 v20, 0xbfb8aa3b, v20
	v_exp_f32_e32 v20, v20
	s_nop 0
	v_mul_f32_e32 v20, v20, v23
	v_cvt_pk_bf16_f32 v20, v20, s0
	ds_write_b16 v24, v20 offset:816
	v_or_b32_e32 v20, 48, v68
	v_sub_u32_e32 v22, v101, v20
	v_sub_u32_e32 v23, 0, v22
	v_max_i32_e32 v23, v22, v23
	v_cvt_f32_u32_e32 v23, v23
	v_cmp_gt_i32_e32 vcc, 0, v22
	v_bitop3_b32 v21, v20, 56, v36 bitop3:0x48
	v_lshlrev_b32_e32 v21, 1, v21
	v_cndmask_b32_e32 v22, v60, v67, vcc
	v_mul_f32_e32 v22, v22, v23
	v_mul_f32_e32 v22, 0xbfb8aa3b, v22
	v_exp_f32_e32 v22, v22
	v_add3_u32 v21, v35, v21, v103
	v_mul_f32_e32 v16, v22, v16
	v_cvt_pk_bf16_f32 v16, v16, s0
	ds_write_b16 v21, v16
	v_sub_u32_e32 v16, v48, v20
	v_sub_u32_e32 v22, 0, v16
	v_max_i32_e32 v22, v16, v22
	v_cvt_f32_u32_e32 v22, v22
	v_cmp_gt_i32_e32 vcc, 0, v16
	s_nop 1
	v_cndmask_b32_e32 v16, v60, v67, vcc
	v_mul_f32_e32 v16, v16, v22
	v_mul_f32_e32 v16, 0xbfb8aa3b, v16
	v_exp_f32_e32 v16, v16
	s_nop 0
	v_mul_f32_e32 v16, v16, v17
	v_cvt_pk_bf16_f32 v16, v16, s0
	ds_write_b16 v21, v16 offset:272
	v_sub_u32_e32 v16, v102, v20
	v_sub_u32_e32 v17, 0, v16
	v_max_i32_e32 v17, v16, v17
	v_cvt_f32_u32_e32 v17, v17
	v_cmp_gt_i32_e32 vcc, 0, v16
	s_nop 1
	v_cndmask_b32_e32 v16, v60, v67, vcc
	v_mul_f32_e32 v16, v16, v17
	v_mul_f32_e32 v16, 0xbfb8aa3b, v16
	v_exp_f32_e32 v16, v16
	s_nop 0
	v_mul_f32_e32 v16, v16, v18
	v_cvt_pk_bf16_f32 v16, v16, s0
	ds_write_b16 v21, v16 offset:544
	v_sub_u32_e32 v16, v100, v20
	v_sub_u32_e32 v17, 0, v16
	v_max_i32_e32 v17, v16, v17
	v_cvt_f32_u32_e32 v17, v17
	v_cmp_gt_i32_e32 vcc, 0, v16
	s_nop 1
	v_cndmask_b32_e32 v16, v60, v67, vcc
	v_mul_f32_e32 v16, v16, v17
	v_sub_u32_e32 v17, v101, v112
	v_sub_u32_e32 v18, 0, v17
	v_max_i32_e32 v18, v17, v18
	v_cvt_f32_u32_e32 v18, v18
	v_mul_f32_e32 v16, 0xbfb8aa3b, v16
	v_cmp_gt_i32_e32 vcc, 0, v17
	v_exp_f32_e32 v16, v16
	s_nop 0
	v_cndmask_b32_e32 v17, v60, v67, vcc
	v_mul_f32_e32 v17, v17, v18
	v_mul_f32_e32 v17, 0xbfb8aa3b, v17
	v_exp_f32_e32 v17, v17
	v_mul_f32_e32 v16, v16, v19
	v_cvt_pk_bf16_f32 v16, v16, s0
	ds_write_b16 v21, v16 offset:816
	v_bitop3_b32 v16, v112, s39, v36 bitop3:0x48
	v_lshlrev_b32_e32 v16, 1, v16
	v_mul_f32_e32 v12, v17, v12
	v_cvt_pk_bf16_f32 v12, v12, s0
	v_add3_u32 v16, v35, v16, v103
	ds_write_b16 v16, v12
	v_sub_u32_e32 v12, v48, v112
	v_sub_u32_e32 v17, 0, v12
	v_max_i32_e32 v17, v12, v17
	v_cvt_f32_u32_e32 v17, v17
	v_cmp_gt_i32_e32 vcc, 0, v12
	s_nop 1
	v_cndmask_b32_e32 v12, v60, v67, vcc
	v_mul_f32_e32 v12, v12, v17
	v_mul_f32_e32 v12, 0xbfb8aa3b, v12
	v_exp_f32_e32 v12, v12
	s_nop 0
	v_mul_f32_e32 v12, v12, v13
	v_cvt_pk_bf16_f32 v12, v12, s0
	ds_write_b16 v16, v12 offset:272
	v_sub_u32_e32 v12, v102, v112
	v_sub_u32_e32 v13, 0, v12
	v_max_i32_e32 v13, v12, v13
	v_cvt_f32_u32_e32 v13, v13
	v_cmp_gt_i32_e32 vcc, 0, v12
	s_nop 1
	v_cndmask_b32_e32 v12, v60, v67, vcc
	v_mul_f32_e32 v12, v12, v13
	v_mul_f32_e32 v12, 0xbfb8aa3b, v12
	v_exp_f32_e32 v12, v12
	s_nop 0
	v_mul_f32_e32 v12, v12, v14
	v_cvt_pk_bf16_f32 v12, v12, s0
	ds_write_b16 v16, v12 offset:544
	v_sub_u32_e32 v12, v100, v112
	v_sub_u32_e32 v13, 0, v12
	v_max_i32_e32 v13, v12, v13
	v_cvt_f32_u32_e32 v13, v13
	v_cmp_gt_i32_e32 vcc, 0, v12
	v_add_u32_e32 v112, s82, v105
	v_add_u32_e32 v105, s82, v117
	v_cndmask_b32_e32 v12, v60, v67, vcc
	v_mul_f32_e32 v12, v12, v13
	v_sub_u32_e32 v13, v101, v110
	v_sub_u32_e32 v14, 0, v13
	v_max_i32_e32 v14, v13, v14
	v_cvt_f32_u32_e32 v14, v14
	v_mul_f32_e32 v12, 0xbfb8aa3b, v12
; #define LAS __attribute__((address_space(3)))
; #define LDS_WAIT() asm volatile("s_waitcnt lgkmcnt(0)" ::: "memory")
; DI void out_unit(const Inputs& in, int l, unsigned char* ws, int half, int u, LAS unsigned char* lds, int tid) {
;     ...
; #pragma unroll
;     for (int cg = 0; cg < 8; ++cg)
; #pragma unroll
;         for (int r = 0; r < 4; ++r) { const int i = 16 * wave + 4 * quad + r, j = 16 * cg + l15, df = i - j;
;             const float fac = df >= 0 ? __expf((float)df * lgf) : __expf((float)(-df) * lgb);
;             ((LAS bf16_t*)Ps)[sw(4 * quad + r, j)] = f2bf(F[cg][r] * fac); }
;     LDS_WAIT();
;     zero8(O); mma16(O, Ps, 0, VTt, lane);
	v_cmp_gt_i32_e32 vcc, 0, v13
	v_exp_f32_e32 v12, v12
	v_add_u32_e32 v117, s82, v124
	v_cndmask_b32_e32 v13, v60, v67, vcc
	v_mul_f32_e32 v13, v13, v14
	v_mul_f32_e32 v13, 0xbfb8aa3b, v13
	v_exp_f32_e32 v13, v13
	v_mul_f32_e32 v12, v12, v15
	v_cvt_pk_bf16_f32 v12, v12, s0
	ds_write_b16 v16, v12 offset:816
	v_bitop3_b32 v12, v110, s40, v36 bitop3:0x48
	v_lshlrev_b32_e32 v12, 1, v12
	v_mul_f32_e32 v8, v13, v8
	v_cvt_pk_bf16_f32 v8, v8, s0
	v_add3_u32 v12, v35, v12, v103
	ds_write_b16 v12, v8
	v_sub_u32_e32 v8, v48, v110
	v_sub_u32_e32 v13, 0, v8
	v_max_i32_e32 v13, v8, v13
	v_cvt_f32_u32_e32 v13, v13
	v_cmp_gt_i32_e32 vcc, 0, v8
	s_nop 1
	v_cndmask_b32_e32 v8, v60, v67, vcc
	v_mul_f32_e32 v8, v8, v13
	v_mul_f32_e32 v8, 0xbfb8aa3b, v8
	v_exp_f32_e32 v8, v8
	s_nop 0
	v_mul_f32_e32 v8, v8, v9
	v_cvt_pk_bf16_f32 v8, v8, s0
	ds_write_b16 v12, v8 offset:272
	v_sub_u32_e32 v8, v102, v110
	v_sub_u32_e32 v9, 0, v8
	v_max_i32_e32 v9, v8, v9
	v_cvt_f32_u32_e32 v9, v9
	v_cmp_gt_i32_e32 vcc, 0, v8
	s_nop 1
	v_cndmask_b32_e32 v8, v60, v67, vcc
	v_mul_f32_e32 v8, v8, v9
	v_mul_f32_e32 v8, 0xbfb8aa3b, v8
	v_exp_f32_e32 v8, v8
	s_nop 0
	v_mul_f32_e32 v8, v8, v10
	v_cvt_pk_bf16_f32 v8, v8, s0
	ds_write_b16 v12, v8 offset:544
	v_sub_u32_e32 v8, v100, v110
	v_sub_u32_e32 v9, 0, v8
	v_max_i32_e32 v9, v8, v9
	v_cvt_f32_u32_e32 v9, v9
	v_cmp_gt_i32_e32 vcc, 0, v8
	v_add_u32_e32 v110, s82, v106
	v_add_u32_e32 v106, s82, v109
	v_cndmask_b32_e32 v8, v60, v67, vcc
	v_mul_f32_e32 v8, v8, v9
	v_sub_u32_e32 v9, v101, v108
	v_sub_u32_e32 v10, 0, v9
	v_max_i32_e32 v10, v9, v10
	v_cvt_f32_u32_e32 v10, v10
	v_mul_f32_e32 v8, 0xbfb8aa3b, v8
	v_cmp_gt_i32_e32 vcc, 0, v9
	v_exp_f32_e32 v8, v8
	v_add_u32_e32 v109, s82, v119
	v_cndmask_b32_e32 v9, v60, v67, vcc
	v_mul_f32_e32 v9, v9, v10
	v_mul_f32_e32 v9, 0xbfb8aa3b, v9
	v_exp_f32_e32 v9, v9
	v_mul_f32_e32 v8, v8, v11
	v_cvt_pk_bf16_f32 v8, v8, s0
	ds_write_b16 v12, v8 offset:816
	v_bitop3_b32 v8, v108, s41, v36 bitop3:0x48
	v_lshlrev_b32_e32 v8, 1, v8
	v_mul_f32_e32 v4, v9, v4
	v_cvt_pk_bf16_f32 v4, v4, s0
	v_add3_u32 v8, v35, v8, v103
	ds_write_b16 v8, v4
	v_sub_u32_e32 v4, v48, v108
	v_sub_u32_e32 v9, 0, v4
	v_max_i32_e32 v9, v4, v9
	v_cvt_f32_u32_e32 v9, v9
	v_cmp_gt_i32_e32 vcc, 0, v4
	v_add_u32_e32 v119, s82, v126
	v_add_u32_e32 v126, s82, v137
	v_cndmask_b32_e32 v4, v60, v67, vcc
	v_mul_f32_e32 v4, v4, v9
	v_mul_f32_e32 v4, 0xbfb8aa3b, v4
	v_exp_f32_e32 v4, v4
	s_nop 0
	v_mul_f32_e32 v4, v4, v5
	v_cvt_pk_bf16_f32 v4, v4, s0
	ds_write_b16 v8, v4 offset:272
	v_sub_u32_e32 v4, v102, v108
	v_sub_u32_e32 v5, 0, v4
	v_max_i32_e32 v5, v4, v5
	v_cvt_f32_u32_e32 v5, v5
	v_cmp_gt_i32_e32 vcc, 0, v4
	s_nop 1
	v_cndmask_b32_e32 v4, v60, v67, vcc
	v_mul_f32_e32 v4, v4, v5
	v_mul_f32_e32 v4, 0xbfb8aa3b, v4
	v_exp_f32_e32 v4, v4
	s_nop 0
	v_mul_f32_e32 v4, v4, v6
	v_cvt_pk_bf16_f32 v4, v4, s0
	ds_write_b16 v8, v4 offset:544
	v_sub_u32_e32 v4, v100, v108
	v_sub_u32_e32 v5, 0, v4
	v_max_i32_e32 v5, v4, v5
	v_cvt_f32_u32_e32 v5, v5
	v_cmp_gt_i32_e32 vcc, 0, v4
	v_add_u32_e32 v108, s82, v107
	v_add_u32_e32 v107, s82, v118
	v_cndmask_b32_e32 v4, v60, v67, vcc
	v_mul_f32_e32 v4, v4, v5
	v_mul_f32_e32 v4, 0xbfb8aa3b, v4
	v_exp_f32_e32 v4, v4
	v_add_u32_e32 v118, s82, v125
	v_add_u32_e32 v125, s82, v132
	v_mul_f32_e32 v4, v4, v7
	v_cvt_pk_bf16_f32 v4, v4, s0
	ds_write_b16 v8, v4 offset:816
	v_or_b32_e32 v4, 0x70, v68
	v_sub_u32_e32 v6, v101, v4
	v_sub_u32_e32 v7, 0, v6
	v_max_i32_e32 v7, v6, v7
	v_cvt_f32_u32_e32 v7, v7
	v_cmp_gt_i32_e32 vcc, 0, v6
	v_bitop3_b32 v5, v4, s0, v36 bitop3:0x48
	v_lshlrev_b32_e32 v5, 1, v5
	v_cndmask_b32_e32 v6, v60, v67, vcc
	v_mul_f32_e32 v6, v6, v7
	v_mul_f32_e32 v6, 0xbfb8aa3b, v6
	v_exp_f32_e32 v6, v6
	v_add3_u32 v5, v35, v5, v103
	v_add_u32_e32 v35, v65, v116
	v_add_u32_e32 v116, s82, v123
	v_mul_f32_e32 v0, v6, v0
	v_cvt_pk_bf16_f32 v0, v0, s0
	ds_write_b16 v5, v0
	v_sub_u32_e32 v0, v48, v4
	v_sub_u32_e32 v6, 0, v0
	v_max_i32_e32 v6, v0, v6
	v_cvt_f32_u32_e32 v6, v6
	v_cmp_gt_i32_e32 vcc, 0, v0
	v_add_u32_e32 v123, s82, v130
	v_add_u32_e32 v130, s82, v32
	v_cndmask_b32_e32 v0, v60, v67, vcc
	v_mul_f32_e32 v0, v0, v6
	v_mul_f32_e32 v0, 0xbfb8aa3b, v0
	v_exp_f32_e32 v0, v0
	v_cvt_f32_i32_e32 v48, v48
	v_mul_f32_e32 v0, v0, v1
	v_cvt_pk_bf16_f32 v0, v0, s0
	ds_write_b16 v5, v0 offset:272
	v_sub_u32_e32 v0, v102, v4
	v_sub_u32_e32 v1, 0, v0
	v_max_i32_e32 v1, v0, v1
	v_cvt_f32_u32_e32 v1, v1
	v_cmp_gt_i32_e32 vcc, 0, v0
	v_mul_f32_e32 v48, v48, v60
	v_mul_f32_e32 v48, 0xbfb8aa3b, v48
	v_cndmask_b32_e32 v0, v60, v67, vcc
	v_mul_f32_e32 v0, v0, v1
	v_mul_f32_e32 v0, 0xbfb8aa3b, v0
	v_exp_f32_e32 v0, v0
	v_exp_f32_e32 v48, v48
	v_mul_f32_e32 v0, v0, v2
	v_cvt_pk_bf16_f32 v0, v0, s0
	ds_write_b16 v5, v0 offset:544
	v_sub_u32_e32 v0, v100, v4
	v_sub_u32_e32 v1, 0, v0
	v_max_i32_e32 v1, v0, v1
	v_cvt_f32_u32_e32 v1, v1
	v_cmp_gt_i32_e32 vcc, 0, v0
	s_nop 1
	v_cndmask_b32_e32 v0, v60, v67, vcc
	v_mul_f32_e32 v0, v0, v1
	v_mul_f32_e32 v0, 0xbfb8aa3b, v0
	v_exp_f32_e32 v0, v0
	s_nop 0
	v_mul_f32_e32 v0, v0, v3
	v_cvt_pk_bf16_f32 v0, v0, s0
	ds_write_b16 v5, v0 offset:816
	s_waitcnt lgkmcnt(0)
	v_add_u32_e32 v0, v65, v104
	ds_read_b128 v[0:3], v0
	ds_read_b128 v[36:39], v49
	v_add_u32_e32 v104, s82, v111
	ds_read_b128 v[4:7], v114
	ds_read_b128 v[8:11], v112
	ds_read_b128 v[12:15], v110
	ds_read_b128 v[16:19], v108
	ds_read_b128 v[20:23], v106
	ds_read_b128 v[24:27], v104
	ds_read_b128 v[28:31], v50
	s_waitcnt lgkmcnt(6)
	v_mfma_f32_16x16x32_bf16 v[4:7], v[0:3], v[4:7], 0
	ds_read_b128 v[40:43], v51
	v_add_u32_e32 v111, s82, v120
	v_add_u32_e32 v120, s82, v127
	s_waitcnt lgkmcnt(6)
; #define LAS __attribute__((address_space(3)))
; DI void stage_state(LAS unsigned char* dst, const bf16_t* src, int tid) {
;     u32x4 wv[4];
; #pragma unroll
;     for (int k = 0; k < 4; ++k) { const int it = tid + 512 * k, e = it >> 4, d0 = (it & 15) * 8; wv[k] = *(const u32x4*)(src + e * 128 + d0); }
; #pragma unroll
;     for (int k = 0; k < 4; ++k) { const int it = tid + 512 * k, e = it >> 4, d0 = (it & 15) * 8; *(LAS u32x4*)(dst + sw(e, d0) * 2) = wv[k]; }
; }
; DI void mma16(f32x4 (&acc)[8], const LAS unsigned char* At, int arow0, const LAS unsigned char* Bt, int lane) {
;     const int l15 = lane & 15, quad = lane >> 4;
; #pragma unroll
;     for (int ks = 0; ks < 4; ++ks) {
;         const bf16x8 a = *(const LAS bf16x8*)(At + sw(arow0 + l15, 32 * ks + 8 * quad) * 2);
; #pragma unroll
;         for (int cg = 0; cg < 8; ++cg) { const bf16x8 b = *(const LAS bf16x8*)(Bt + sw(16 * cg + l15, 32 * ks + 8 * quad) * 2);
;             acc[cg] = __builtin_amdgcn_mfma_f32_16x16x32_bf16(a, b, acc[cg], 0, 0, 0); }
;     }
; }
; DI void out_unit(const Inputs& in, int l, unsigned char* ws, int half, int u, LAS unsigned char* lds, int tid) {
;     ...
;     zero8(O); mma16(O, Ps, 0, VTt, lane);
;     __syncthreads();
;     stage_state(Kt, SS + (size_t)(u * 2 + 0) * 16384, tid); stage_state(VTt, SS + (size_t)(u * 2 + 1) * 16384, tid);
;     __syncthreads();
	v_mfma_f32_16x16x32_bf16 v[8:11], v[0:3], v[8:11], 0
	v_add_u32_e32 v127, s82, v138
	s_waitcnt lgkmcnt(5)
	v_mfma_f32_16x16x32_bf16 v[12:15], v[0:3], v[12:15], 0
	s_waitcnt lgkmcnt(4)
	v_mfma_f32_16x16x32_bf16 v[16:19], v[0:3], v[16:19], 0
	s_waitcnt lgkmcnt(3)
	v_mfma_f32_16x16x32_bf16 v[20:23], v[0:3], v[20:23], 0
	s_waitcnt lgkmcnt(2)
	v_mfma_f32_16x16x32_bf16 v[24:27], v[0:3], v[24:27], 0
	s_waitcnt lgkmcnt(1)
	v_mfma_f32_16x16x32_bf16 v[28:31], v[0:3], v[28:31], 0
	v_mfma_f32_16x16x32_bf16 v[0:3], v[0:3], v[36:39], 0
	ds_read_b128 v[36:39], v35
	v_add_u32_e32 v35, v65, v124
	v_add_u32_e32 v124, s82, v131
	s_waitcnt lgkmcnt(0)
	v_mfma_f32_16x16x32_bf16 v[4:7], v[36:39], v[40:43], v[4:7]
	ds_read_b128 v[40:43], v105
	v_add_u32_e32 v131, s82, v33
	v_lshl_add_u64 v[32:33], s[16:17], 0, v[176:177]
	s_waitcnt lgkmcnt(0)
	v_mfma_f32_16x16x32_bf16 v[8:11], v[36:39], v[40:43], v[8:11]
	ds_read_b128 v[40:43], v107
	s_add_i32 s16, s12, 1
	s_ashr_i32 s17, s16, 31
	s_waitcnt lgkmcnt(0)
	v_mfma_f32_16x16x32_bf16 v[12:15], v[36:39], v[40:43], v[12:15]
	ds_read_b128 v[40:43], v109
	s_lshl_b64 s[16:17], s[16:17], 15
	s_add_u32 s16, s22, s16
	s_waitcnt lgkmcnt(0)
	v_mfma_f32_16x16x32_bf16 v[16:19], v[36:39], v[40:43], v[16:19]
	ds_read_b128 v[40:43], v111
	s_addc_u32 s17, s23, s17
	s_add_i32 s26, s26, s18
	s_waitcnt lgkmcnt(0)
	v_mfma_f32_16x16x32_bf16 v[20:23], v[36:39], v[40:43], v[20:23]
	ds_read_b128 v[40:43], v113
	s_add_i32 s12, s12, s25
	s_cmpk_gt_i32 s26, 0x1ff
	s_waitcnt lgkmcnt(0)
	v_mfma_f32_16x16x32_bf16 v[24:27], v[36:39], v[40:43], v[24:27]
	ds_read_b128 v[40:43], v115
	s_waitcnt lgkmcnt(0)
	v_mfma_f32_16x16x32_bf16 v[28:31], v[36:39], v[40:43], v[28:31]
	ds_read_b128 v[40:43], v116
	s_waitcnt lgkmcnt(0)
	v_mfma_f32_16x16x32_bf16 v[0:3], v[36:39], v[40:43], v[0:3]
	ds_read_b128 v[36:39], v35
	ds_read_b128 v[40:43], v117
	s_waitcnt lgkmcnt(0)
	v_mfma_f32_16x16x32_bf16 v[4:7], v[36:39], v[40:43], v[4:7]
	ds_read_b128 v[40:43], v118
	s_waitcnt lgkmcnt(0)
	v_mfma_f32_16x16x32_bf16 v[8:11], v[36:39], v[40:43], v[8:11]
	ds_read_b128 v[40:43], v119
	s_waitcnt lgkmcnt(0)
	v_mfma_f32_16x16x32_bf16 v[12:15], v[36:39], v[40:43], v[12:15]
	ds_read_b128 v[40:43], v120
	s_waitcnt lgkmcnt(0)
	v_mfma_f32_16x16x32_bf16 v[16:19], v[36:39], v[40:43], v[16:19]
	ds_read_b128 v[40:43], v121
	s_waitcnt lgkmcnt(0)
	v_mfma_f32_16x16x32_bf16 v[20:23], v[36:39], v[40:43], v[20:23]
	ds_read_b128 v[40:43], v122
	s_waitcnt lgkmcnt(0)
	v_mfma_f32_16x16x32_bf16 v[24:27], v[36:39], v[40:43], v[24:27]
	ds_read_b128 v[40:43], v123
	s_waitcnt lgkmcnt(0)
	v_mfma_f32_16x16x32_bf16 v[28:31], v[36:39], v[40:43], v[28:31]
	ds_read_b128 v[40:43], v124
	s_waitcnt lgkmcnt(0)
	v_mfma_f32_16x16x32_bf16 v[36:39], v[36:39], v[40:43], v[0:3]
	s_nop 2
	v_add_u32_e32 v0, v65, v132
	ds_read_b128 v[40:43], v0
	ds_read_b128 v[0:3], v125
	s_waitcnt lgkmcnt(0)
	v_mfma_f32_16x16x32_bf16 v[0:3], v[40:43], v[0:3], v[4:7]
	s_nop 2
	ds_read_b128 v[4:7], v126
	v_add_u32_e32 v132, s82, v34
	v_and_b32_e32 v34, 0xffffff80, v91
	s_waitcnt lgkmcnt(0)
	v_mfma_f32_16x16x32_bf16 v[4:7], v[40:43], v[4:7], v[8:11]
	v_ashrrev_i32_e32 v35, 31, v34
	s_nop 1
	ds_read_b128 v[8:11], v127
	v_add_u32_e32 v91, 0, v58
	s_waitcnt lgkmcnt(0)
	v_mfma_f32_16x16x32_bf16 v[8:11], v[40:43], v[8:11], v[12:15]
	s_nop 2
	ds_read_b128 v[12:15], v128
	s_waitcnt lgkmcnt(0)
	v_mfma_f32_16x16x32_bf16 v[12:15], v[40:43], v[12:15], v[16:19]
	s_nop 2
	ds_read_b128 v[16:19], v129
	s_waitcnt lgkmcnt(0)
	v_mfma_f32_16x16x32_bf16 v[16:19], v[40:43], v[16:19], v[20:23]
	s_nop 2
	ds_read_b128 v[20:23], v130
	s_waitcnt lgkmcnt(0)
	v_mfma_f32_16x16x32_bf16 v[20:23], v[40:43], v[20:23], v[24:27]
	s_nop 2
	ds_read_b128 v[24:27], v131
	s_waitcnt lgkmcnt(0)
	v_mfma_f32_16x16x32_bf16 v[24:27], v[40:43], v[24:27], v[28:31]
	s_nop 2
	ds_read_b128 v[28:31], v132
	s_waitcnt lgkmcnt(0)
	s_barrier
	v_mfma_f32_16x16x32_bf16 v[28:31], v[40:43], v[28:31], v[36:39]
	s_nop 2
	v_lshlrev_b64 v[36:37], 1, v[34:35]
	v_lshl_add_u64 v[38:39], v[32:33], 0, v[36:37]
	global_load_dwordx4 v[44:47], v[38:39], off
	v_add_u32_e32 v38, 0x1000, v34
	v_ashrrev_i32_e32 v39, 31, v38
	v_lshlrev_b64 v[38:39], 1, v[38:39]
	v_lshl_add_u64 v[40:41], v[32:33], 0, v[38:39]
	global_load_dwordx4 v[138:141], v[40:41], off
	v_add_u32_e32 v40, 0x2000, v34
	v_ashrrev_i32_e32 v41, 31, v40
	v_lshlrev_b64 v[40:41], 1, v[40:41]
	v_lshl_add_u64 v[42:43], v[32:33], 0, v[40:41]
	v_add_u32_e32 v34, 0x3000, v34
	global_load_dwordx4 v[142:145], v[42:43], off
	v_ashrrev_i32_e32 v35, 31, v34
	v_lshlrev_b64 v[42:43], 1, v[34:35]
	v_lshl_add_u64 v[32:33], v[32:33], 0, v[42:43]
	global_load_dwordx4 v[32:35], v[32:33], off
	v_lshl_add_u64 v[174:175], s[16:17], 0, v[176:177]
	v_lshl_add_u64 v[166:167], v[174:175], 0, v[36:37]
	global_load_dwordx4 v[190:193], v[166:167], off
	v_lshl_add_u64 v[166:167], v[174:175], 0, v[38:39]
	global_load_dwordx4 v[194:197], v[166:167], off
	v_lshl_add_u64 v[166:167], v[174:175], 0, v[40:41]
	global_load_dwordx4 v[198:201], v[166:167], off
	v_lshl_add_u64 v[166:167], v[174:175], 0, v[42:43]
	global_load_dwordx4 v[202:205], v[166:167], off
	s_waitcnt vmcnt(7)
	ds_write_b128 v91, v[44:47] offset:34816
	v_mul_lo_u32 v44, v56, s1
	v_add_lshl_u32 v56, v135, v44, 1
	v_add_u32_e32 v44, 0, v56
	s_waitcnt vmcnt(6)
	ds_write_b128 v44, v[138:141] offset:34816
	v_mul_lo_u32 v44, v54, s1
	v_add_lshl_u32 v54, v136, v44, 1
	v_add_u32_e32 v44, 0, v54
	s_waitcnt vmcnt(5)
	ds_write_b128 v44, v[142:145] offset:34816
	v_mul_lo_u32 v44, v52, s1
	v_add_lshl_u32 v52, v133, v44, 1
	v_add_u32_e32 v44, 0, v52
	s_waitcnt vmcnt(4)
	ds_write_b128 v44, v[32:35] offset:34816
	v_add_u32_e32 v40, s82, v58
	s_waitcnt vmcnt(3)
	v_mov_b32_e32 v44, v190
	v_mov_b32_e32 v45, v191
	v_mov_b32_e32 v46, v192
	v_mov_b32_e32 v47, v193
	ds_write_b128 v40, v[44:47]
	v_add_u32_e32 v40, s82, v56
	s_waitcnt vmcnt(2)
	v_mov_b32_e32 v36, v194
	v_mov_b32_e32 v37, v195
	v_mov_b32_e32 v38, v196
	v_mov_b32_e32 v39, v197
	ds_write_b128 v40, v[36:39]
	v_add_u32_e32 v36, s82, v54
	s_waitcnt vmcnt(1)
	v_mov_b32_e32 v134, v198
	v_mov_b32_e32 v135, v199
	v_mov_b32_e32 v136, v200
	v_mov_b32_e32 v137, v201
	ds_write_b128 v36, v[134:137]
	v_add_u32_e32 v36, s82, v52
	s_waitcnt vmcnt(0)
	v_mov_b32_e32 v32, v202
	v_mov_b32_e32 v33, v203
	v_mov_b32_e32 v34, v204
	v_mov_b32_e32 v35, v205
	ds_write_b128 v36, v[32:35]
	s_waitcnt lgkmcnt(0)
	s_barrier
; #define LAS __attribute__((address_space(3)))
; DI void mma16(f32x4 (&acc)[8], const LAS unsigned char* At, int arow0, const LAS unsigned char* Bt, int lane) {
;     ...
;     for (int ks = 0; ks < 4; ++ks) {
;         const bf16x8 a = *(const LAS bf16x8*)(At + sw(arow0 + l15, 32 * ks + 8 * quad) * 2);
; #pragma unroll
;         for (int cg = 0; cg < 8; ++cg) { const bf16x8 b = *(const LAS bf16x8*)(Bt + sw(16 * cg + l15, 32 * ks + 8 * quad) * 2);
;             acc[cg] = __builtin_amdgcn_mfma_f32_16x16x32_bf16(a, b, acc[cg], 0, 0, 0); }
; DI void out_unit(const Inputs& in, int l, unsigned char* ws, int half, int u, LAS unsigned char* lds, int tid) {
;     ...
;     zero8(F); mma16(F, Qt, 16 * wave, Kt, lane);
; #pragma unroll
;     for (int r = 0; r < 4; ++r) { const int i = 16 * wave + 4 * quad + r; const float qwf = __expf((float)(i + 1) * lgf);
; #pragma unroll
;         for (int cg = 0; cg < 8; ++cg) O[cg][r] += qwf * F[cg][r]; }
	ds_read_b128 v[32:35], v53
	ds_read_b128 v[36:39], v55 offset:34816
	s_waitcnt lgkmcnt(0)
	v_mfma_f32_16x16x32_bf16 v[40:43], v[32:35], v[36:39], 0
	ds_read_b128 v[36:39], v57 offset:34816
	s_waitcnt lgkmcnt(0)
	v_mfma_f32_16x16x32_bf16 v[44:47], v[32:35], v[36:39], 0
	ds_read_b128 v[36:39], v59 offset:34816
	s_waitcnt lgkmcnt(0)
	v_mfma_f32_16x16x32_bf16 v[52:55], v[32:35], v[36:39], 0
	ds_read_b128 v[36:39], v61 offset:34816
	s_waitcnt lgkmcnt(0)
	v_mfma_f32_16x16x32_bf16 v[56:59], v[32:35], v[36:39], 0
	ds_read_b128 v[36:39], v62 offset:34816
	s_waitcnt lgkmcnt(0)
	v_mfma_f32_16x16x32_bf16 v[134:137], v[32:35], v[36:39], 0
	ds_read_b128 v[36:39], v63 offset:34816
	s_waitcnt lgkmcnt(0)
	v_mfma_f32_16x16x32_bf16 v[138:141], v[32:35], v[36:39], 0
	ds_read_b128 v[36:39], v70 offset:34816
	s_waitcnt lgkmcnt(0)
	v_mfma_f32_16x16x32_bf16 v[142:145], v[32:35], v[36:39], 0
	ds_read_b128 v[36:39], v71 offset:34816
	s_waitcnt lgkmcnt(0)
	v_mfma_f32_16x16x32_bf16 v[146:149], v[32:35], v[36:39], 0
	ds_read_b128 v[36:39], v72
	ds_read_b128 v[70:73], v73 offset:34816
	s_waitcnt lgkmcnt(0)
	v_mfma_f32_16x16x32_bf16 v[70:73], v[36:39], v[70:73], v[40:43]
	s_nop 2
	ds_read_b128 v[40:43], v74 offset:34816
	s_waitcnt lgkmcnt(0)
	v_mfma_f32_16x16x32_bf16 v[44:47], v[36:39], v[40:43], v[44:47]
	ds_read_b128 v[40:43], v75 offset:34816
	s_waitcnt lgkmcnt(0)
	v_mfma_f32_16x16x32_bf16 v[52:55], v[36:39], v[40:43], v[52:55]
	ds_read_b128 v[40:43], v76 offset:34816
	s_waitcnt lgkmcnt(0)
	v_mfma_f32_16x16x32_bf16 v[56:59], v[36:39], v[40:43], v[56:59]
	ds_read_b128 v[40:43], v77 offset:34816
	s_waitcnt lgkmcnt(0)
	v_mfma_f32_16x16x32_bf16 v[74:77], v[36:39], v[40:43], v[134:137]
	ds_read_b128 v[40:43], v78 offset:34816
	s_waitcnt lgkmcnt(0)
	v_mfma_f32_16x16x32_bf16 v[134:137], v[36:39], v[40:43], v[138:141]
	ds_read_b128 v[40:43], v79 offset:34816
	s_waitcnt lgkmcnt(0)
	v_mfma_f32_16x16x32_bf16 v[138:141], v[36:39], v[40:43], v[142:145]
	ds_read_b128 v[40:43], v80 offset:34816
	s_waitcnt lgkmcnt(0)
	v_mfma_f32_16x16x32_bf16 v[142:145], v[36:39], v[40:43], v[146:149]
	ds_read_b128 v[40:43], v81
	ds_read_b128 v[78:81], v82 offset:34816
	s_waitcnt lgkmcnt(0)
	v_mfma_f32_16x16x32_bf16 v[70:73], v[40:43], v[78:81], v[70:73]
	ds_read_b128 v[78:81], v83 offset:34816
	s_waitcnt lgkmcnt(0)
	v_mfma_f32_16x16x32_bf16 v[78:81], v[40:43], v[78:81], v[44:47]
	s_nop 2
	ds_read_b128 v[44:47], v84 offset:34816
	s_waitcnt lgkmcnt(0)
	v_mfma_f32_16x16x32_bf16 v[52:55], v[40:43], v[44:47], v[52:55]
	ds_read_b128 v[44:47], v85 offset:34816
	s_waitcnt lgkmcnt(0)
	v_mfma_f32_16x16x32_bf16 v[56:59], v[40:43], v[44:47], v[56:59]
	ds_read_b128 v[44:47], v86 offset:34816
	s_waitcnt lgkmcnt(0)
	v_mfma_f32_16x16x32_bf16 v[74:77], v[40:43], v[44:47], v[74:77]
	ds_read_b128 v[44:47], v87 offset:34816
	s_waitcnt lgkmcnt(0)
	v_mfma_f32_16x16x32_bf16 v[82:85], v[40:43], v[44:47], v[134:137]
	ds_read_b128 v[44:47], v88 offset:34816
	s_waitcnt lgkmcnt(0)
	v_mfma_f32_16x16x32_bf16 v[134:137], v[40:43], v[44:47], v[138:141]
	ds_read_b128 v[44:47], v89 offset:34816
	s_waitcnt lgkmcnt(0)
	v_mfma_f32_16x16x32_bf16 v[86:89], v[40:43], v[44:47], v[142:145]
	ds_read_b128 v[44:47], v90
	ds_read_b128 v[138:141], v92 offset:34816
	ds_read_b128 v[90:93], v93 offset:34816
	s_waitcnt lgkmcnt(0)
	v_mfma_f32_16x16x32_bf16 v[78:81], v[44:47], v[90:93], v[78:81]
	ds_read_b128 v[90:93], v94 offset:34816
	s_waitcnt lgkmcnt(0)
	v_mfma_f32_16x16x32_bf16 v[52:55], v[44:47], v[90:93], v[52:55]
	ds_read_b128 v[90:93], v95 offset:34816
	s_waitcnt lgkmcnt(0)
	v_mfma_f32_16x16x32_bf16 v[56:59], v[44:47], v[90:93], v[56:59]
	ds_read_b128 v[90:93], v96 offset:34816
	s_waitcnt lgkmcnt(0)
	v_mfma_f32_16x16x32_bf16 v[74:77], v[44:47], v[90:93], v[74:77]
	ds_read_b128 v[90:93], v97 offset:34816
	ds_read_b128 v[94:97], v99 offset:34816
	s_nop 2
	v_fma_f32 v12, v48, v56, v12
	s_waitcnt lgkmcnt(1)
	v_mfma_f32_16x16x32_bf16 v[82:85], v[44:47], v[90:93], v[82:85]
	ds_read_b128 v[90:93], v98 offset:34816
	v_fma_f32 v16, v48, v74, v16
	v_mfma_f32_16x16x32_bf16 v[70:73], v[44:47], v[138:141], v[70:73]
	s_nop 4
	v_fma_f32 v20, v48, v82, v20
	s_waitcnt lgkmcnt(1)
	v_mfma_f32_16x16x32_bf16 v[86:89], v[44:47], v[94:97], v[86:89]
	v_fma_f32 v96, v48, v52, v8
	v_fma_f32 v94, v48, v70, v0
	v_cvt_f32_i32_e32 v0, v102
	s_waitcnt lgkmcnt(0)
	v_mfma_f32_16x16x32_bf16 v[90:93], v[44:47], v[90:93], v[134:137]
	v_fma_f32 v95, v48, v78, v4
	s_nop 1
	v_fma_f32 v28, v48, v86, v28
	v_mul_f32_e32 v0, v0, v60
	v_mul_f32_e32 v0, 0xbfb8aa3b, v0
	v_exp_f32_e32 v0, v0
	s_nop 0
	v_fma_f32 v24, v48, v90, v24
	v_fma_f32 v90, v0, v71, v1
	v_fma_f32 v97, v0, v79, v5
	v_fma_f32 v98, v0, v53, v9
	v_fma_f32 v13, v0, v57, v13
	v_fma_f32 v17, v0, v75, v17
	v_fma_f32 v21, v0, v83, v21
	v_fma_f32 v25, v0, v91, v25
	v_fma_f32 v29, v0, v87, v29
	v_cvt_f32_i32_e32 v0, v100
	v_mul_f32_e32 v0, v0, v60
	v_mul_f32_e32 v0, 0xbfb8aa3b, v0
	v_exp_f32_e32 v0, v0
	s_nop 0
	v_fma_f32 v8, v0, v80, v6
	v_fma_f32 v6, v0, v54, v10
	v_add_u32_e32 v10, 4, v101
	v_cvt_f32_i32_e32 v10, v10
	v_fma_f32 v9, v0, v72, v2
	v_fma_f32 v5, v0, v58, v14
	v_fma_f32 v4, v0, v76, v18
	v_mul_f32_e32 v10, v10, v60
	v_mul_f32_e32 v10, 0xbfb8aa3b, v10
	v_exp_f32_e32 v10, v10
	v_fma_f32 v2, v0, v84, v22
	v_fma_f32 v1, v0, v92, v26
	v_fma_f32 v0, v0, v88, v30
	v_fmac_f32_e32 v11, v10, v55
	ds_read_b128 v[52:55], v114
	v_fmac_f32_e32 v7, v10, v81
	v_fmac_f32_e32 v23, v10, v85
	v_fmac_f32_e32 v31, v10, v89
	ds_read_b128 v[78:81], v104
	ds_read_b128 v[82:85], v50
	ds_read_b128 v[86:89], v49
	ds_read_b128 v[48:51], v51
	v_fmac_f32_e32 v15, v10, v59
	s_waitcnt lgkmcnt(4)
; #define LAS __attribute__((address_space(3)))
; DI void out_unit(const Inputs& in, int l, unsigned char* ws, int half, int u, LAS unsigned char* lds, int tid) {
;     ...
;     zero8(F); mma16(F, Qt, 16 * wave, VTt, lane);
;     LAS bf16_t* Pn = (LAS bf16_t*)Ps;
; #pragma unroll
;     for (int r = 0; r < 4; ++r) { const int i = 16 * wave + 4 * quad + r; const float qwb = __expf((float)(128 - i) * lgb);
;         float sm = 0.f;
; #pragma unroll
;         for (int cg = 0; cg < 8; ++cg) { O[cg][r] += qwb * F[cg][r]; sm += O[cg][r]; }
;         sm += __shfl_xor(sm, 1); sm += __shfl_xor(sm, 2); sm += __shfl_xor(sm, 4); sm += __shfl_xor(sm, 8);
;         const float mean = sm * (1.f / 128.f); float vs = 0.f;
; #pragma unroll
;         for (int cg = 0; cg < 8; ++cg) { const float dd = O[cg][r] - mean; vs += dd * dd; }
;         vs += __shfl_xor(vs, 1); vs += __shfl_xor(vs, 2); vs += __shfl_xor(vs, 4); vs += __shfl_xor(vs, 8);
;         const float rinv = __builtin_amdgcn_rsqf(vs * (1.f / 128.f) + EPS);
	v_mfma_f32_16x16x32_bf16 v[52:55], v[32:35], v[52:55], 0
	ds_read_b128 v[56:59], v112
	ds_read_b128 v[60:63], v110
	v_fmac_f32_e32 v19, v10, v77
	ds_read_b128 v[74:77], v106
	s_waitcnt lgkmcnt(3)
	v_mfma_f32_16x16x32_bf16 v[48:51], v[36:39], v[48:51], v[52:55]
	v_fmac_f32_e32 v3, v10, v73
	ds_read_b128 v[70:73], v108
	v_sub_u32_e32 v14, 0x80, v101
	ds_read_b128 v[52:55], v105
	s_waitcnt lgkmcnt(4)
	v_mfma_f32_16x16x32_bf16 v[56:59], v[32:35], v[56:59], 0
	v_cvt_f32_i32_e32 v14, v14
	v_fmac_f32_e32 v27, v10, v93
	v_lshlrev_b32_e32 v10, 1, v68
	s_waitcnt lgkmcnt(0)
	v_mfma_f32_16x16x32_bf16 v[52:55], v[36:39], v[52:55], v[56:59]
	v_mul_f32_e32 v14, v14, v67
	v_mul_f32_e32 v14, 0xbfb8aa3b, v14
	v_exp_f32_e32 v14, v14
	ds_read_b128 v[56:59], v107
	v_mfma_f32_16x16x32_bf16 v[60:63], v[32:35], v[60:63], 0
	v_add3_u32 v10, v65, v10, v103
	s_waitcnt lgkmcnt(0)
	v_mfma_f32_16x16x32_bf16 v[56:59], v[36:39], v[56:59], v[60:63]
	v_mfma_f32_16x16x32_bf16 v[70:73], v[32:35], v[70:73], 0
	s_nop 3
	ds_read_b128 v[60:63], v109
	s_waitcnt lgkmcnt(0)
	v_mfma_f32_16x16x32_bf16 v[60:63], v[36:39], v[60:63], v[70:73]
	s_nop 2
	ds_read_b128 v[70:73], v111
	v_mfma_f32_16x16x32_bf16 v[74:77], v[32:35], v[74:77], 0
	s_waitcnt lgkmcnt(0)
	v_mfma_f32_16x16x32_bf16 v[70:73], v[36:39], v[70:73], v[74:77]
	v_mfma_f32_16x16x32_bf16 v[78:81], v[32:35], v[78:81], 0
	s_nop 4
	ds_read_b128 v[74:77], v113
	s_waitcnt lgkmcnt(0)
	v_mfma_f32_16x16x32_bf16 v[74:77], v[36:39], v[74:77], v[78:81]
	s_nop 2
	ds_read_b128 v[78:81], v115
	v_mfma_f32_16x16x32_bf16 v[82:85], v[32:35], v[82:85], 0
	s_waitcnt lgkmcnt(0)
	v_mfma_f32_16x16x32_bf16 v[78:81], v[36:39], v[78:81], v[82:85]
	v_mfma_f32_16x16x32_bf16 v[32:35], v[32:35], v[86:89], 0
	s_nop 4
	ds_read_b128 v[82:85], v116
	s_waitcnt lgkmcnt(0)
	v_mfma_f32_16x16x32_bf16 v[32:35], v[36:39], v[82:85], v[32:35]
	ds_read_b128 v[36:39], v117
	s_waitcnt lgkmcnt(0)
	v_mfma_f32_16x16x32_bf16 v[36:39], v[40:43], v[36:39], v[48:51]
	s_nop 2
	ds_read_b128 v[48:51], v118
	s_waitcnt lgkmcnt(0)
	v_mfma_f32_16x16x32_bf16 v[48:51], v[40:43], v[48:51], v[52:55]
	s_nop 2
	ds_read_b128 v[52:55], v119
	s_waitcnt lgkmcnt(0)
	v_mfma_f32_16x16x32_bf16 v[52:55], v[40:43], v[52:55], v[56:59]
	s_nop 2
	ds_read_b128 v[56:59], v120
	s_waitcnt lgkmcnt(0)
	v_mfma_f32_16x16x32_bf16 v[56:59], v[40:43], v[56:59], v[60:63]
	s_nop 2
	ds_read_b128 v[60:63], v121
	s_waitcnt lgkmcnt(0)
	v_mfma_f32_16x16x32_bf16 v[60:63], v[40:43], v[60:63], v[70:73]
	s_nop 2
	ds_read_b128 v[70:73], v122
	s_waitcnt lgkmcnt(0)
	v_mfma_f32_16x16x32_bf16 v[70:73], v[40:43], v[70:73], v[74:77]
	s_nop 2
	ds_read_b128 v[74:77], v123
	s_waitcnt lgkmcnt(0)
	v_mfma_f32_16x16x32_bf16 v[74:77], v[40:43], v[74:77], v[78:81]
	s_nop 2
	ds_read_b128 v[78:81], v124
	s_waitcnt lgkmcnt(0)
	v_mfma_f32_16x16x32_bf16 v[78:81], v[40:43], v[78:81], v[32:35]
	s_nop 2
	ds_read_b128 v[32:35], v125
	ds_read_b128 v[40:43], v127
	s_waitcnt lgkmcnt(1)
	v_mfma_f32_16x16x32_bf16 v[32:35], v[44:47], v[32:35], v[36:39]
	s_nop 2
	ds_read_b128 v[36:39], v126
	s_waitcnt lgkmcnt(1)
	v_mfma_f32_16x16x32_bf16 v[40:43], v[44:47], v[40:43], v[52:55]
	s_nop 1
	v_fmac_f32_e32 v94, v14, v32
	v_add_f32_e32 v18, 0, v94
	ds_read_b128 v[52:55], v129
	s_waitcnt lgkmcnt(1)
	v_mfma_f32_16x16x32_bf16 v[36:39], v[44:47], v[36:39], v[48:51]
	s_nop 0
	v_fmac_f32_e32 v96, v14, v40
	s_nop 0
	ds_read_b128 v[48:51], v128
	s_waitcnt lgkmcnt(1)
	v_mfma_f32_16x16x32_bf16 v[52:55], v[44:47], v[52:55], v[60:63]
	s_nop 1
	v_fmac_f32_e32 v95, v14, v36
	v_add_f32_e32 v18, v18, v95
	v_add_f32_e32 v18, v18, v96
	ds_read_b128 v[60:63], v131
	s_waitcnt lgkmcnt(1)
	v_mfma_f32_16x16x32_bf16 v[48:51], v[44:47], v[48:51], v[56:59]
	v_fmac_f32_e32 v16, v14, v52
	s_nop 1
	ds_read_b128 v[56:59], v130
	s_waitcnt lgkmcnt(0)
	v_mfma_f32_16x16x32_bf16 v[56:59], v[44:47], v[56:59], v[70:73]
	s_nop 2
	ds_read_b128 v[70:73], v132
	v_fmac_f32_e32 v12, v14, v48
	v_add_f32_e32 v18, v18, v12
	v_mfma_f32_16x16x32_bf16 v[60:63], v[44:47], v[60:63], v[74:77]
	v_add_f32_e32 v18, v18, v16
	v_fmac_f32_e32 v20, v14, v56
	v_add_f32_e32 v18, v18, v20
	s_waitcnt lgkmcnt(0)
	v_mfma_f32_16x16x32_bf16 v[44:47], v[44:47], v[70:73], v[78:81]
	s_nop 2
	v_fmac_f32_e32 v24, v14, v60
	v_add_f32_e32 v18, v18, v24
	s_nop 2
	v_fmac_f32_e32 v28, v14, v44
	v_add_f32_e32 v14, v18, v28
	ds_bpermute_b32 v18, v206, v14
	s_waitcnt lgkmcnt(0)
	v_add_f32_e32 v14, v14, v18
	ds_bpermute_b32 v18, v207, v14
	s_waitcnt lgkmcnt(0)
	v_add_f32_e32 v14, v14, v18
	ds_bpermute_b32 v18, v208, v14
	s_waitcnt lgkmcnt(0)
	v_add_f32_e32 v14, v14, v18
	ds_bpermute_b32 v18, v209, v14
	s_waitcnt lgkmcnt(0)
	v_add_f32_e32 v14, v14, v18
	v_fmac_f32_e32 v95, 0xbc000000, v14
	v_fmac_f32_e32 v94, 0xbc000000, v14
	v_mul_f32_e32 v18, v95, v95
	v_fmac_f32_e32 v18, v94, v94
	v_fmac_f32_e32 v96, 0xbc000000, v14
	v_fmac_f32_e32 v18, v96, v96
	v_fmac_f32_e32 v12, 0xbc000000, v14
	v_fmac_f32_e32 v18, v12, v12
	v_fmac_f32_e32 v16, 0xbc000000, v14
	v_fmac_f32_e32 v18, v16, v16
	v_fmac_f32_e32 v20, 0xbc000000, v14
	v_fmac_f32_e32 v18, v20, v20
	v_fmac_f32_e32 v24, 0xbc000000, v14
	v_fmac_f32_e32 v18, v24, v24
	v_fmac_f32_e32 v28, 0xbc000000, v14
	v_fmac_f32_e32 v18, v28, v28
	ds_bpermute_b32 v14, v206, v18
	s_waitcnt lgkmcnt(0)
	v_add_f32_e32 v14, v18, v14
	ds_bpermute_b32 v18, v207, v14
	s_waitcnt lgkmcnt(0)
	v_add_f32_e32 v14, v14, v18
	ds_bpermute_b32 v18, v208, v14
	s_waitcnt lgkmcnt(0)
	v_add_f32_e32 v14, v14, v18
	ds_bpermute_b32 v18, v209, v14
	s_waitcnt lgkmcnt(0)
; DI void out_unit(const Inputs& in, int l, unsigned char* ws, int half, int u, LAS unsigned char* lds, int tid) {
;     ...
;     for (int r = 0; r < 4; ++r) { const int i = 16 * wave + 4 * quad + r; const float qwb = __expf((float)(128 - i) * lgb);
;         float sm = 0.f;
; #pragma unroll
;         for (int cg = 0; cg < 8; ++cg) { O[cg][r] += qwb * F[cg][r]; sm += O[cg][r]; }
;         sm += __shfl_xor(sm, 1); sm += __shfl_xor(sm, 2); sm += __shfl_xor(sm, 4); sm += __shfl_xor(sm, 8);
;         const float mean = sm * (1.f / 128.f); float vs = 0.f;
; #pragma unroll
;         for (int cg = 0; cg < 8; ++cg) { const float dd = O[cg][r] - mean; vs += dd * dd; }
;         vs += __shfl_xor(vs, 1); vs += __shfl_xor(vs, 2); vs += __shfl_xor(vs, 4); vs += __shfl_xor(vs, 8);
;         const float rinv = __builtin_amdgcn_rsqf(vs * (1.f / 128.f) + EPS);
; #pragma unroll
;         for (int cg = 0; cg < 8; ++cg) Pn[(4 * quad + r) * TS + 16 * cg + l15] = f2bf((O[cg][r] - mean) * rinv);
	v_add_f32_e32 v14, v14, v18
	v_fmamk_f32 v14, v14, 0x3c000000, v217
	v_rsq_f32_e32 v14, v14
	s_nop 0
	v_mul_f32_e32 v12, v12, v14
	v_cvt_pk_bf16_f32 v12, v12, s0
	ds_write_b16 v10, v12 offset:96
	v_mul_f32_e32 v12, v16, v14
	v_cvt_pk_bf16_f32 v12, v12, s0
	ds_write_b16 v10, v12 offset:128
	v_mul_f32_e32 v12, v20, v14
	v_cvt_pk_bf16_f32 v12, v12, s0
	ds_write_b16 v10, v12 offset:160
	v_mul_f32_e32 v12, v24, v14
	v_cvt_pk_bf16_f32 v12, v12, s0
	ds_write_b16 v10, v12 offset:192
	v_mul_f32_e32 v12, v28, v14
	v_cvt_pk_bf16_f32 v12, v12, s0
	ds_write_b16 v10, v12 offset:224
	v_sub_u32_e32 v12, 0x7f, v101
	v_cvt_f32_i32_e32 v12, v12
	v_mul_f32_e32 v18, v94, v14
	v_cvt_pk_bf16_f32 v18, v18, s0
	ds_write_b16 v10, v18
	v_mul_f32_e32 v12, v12, v67
	v_mul_f32_e32 v12, 0xbfb8aa3b, v12
	v_exp_f32_e32 v12, v12
	v_mul_f32_e32 v18, v95, v14
	v_cvt_pk_bf16_f32 v18, v18, s0
	ds_write_b16 v10, v18 offset:32
	v_fmac_f32_e32 v90, v12, v33
	v_mul_f32_e32 v18, v96, v14
	v_add_f32_e32 v14, 0, v90
	v_fmac_f32_e32 v97, v12, v37
	v_add_f32_e32 v14, v14, v97
	v_fmac_f32_e32 v98, v12, v41
	v_add_f32_e32 v14, v14, v98
	v_fmac_f32_e32 v13, v12, v49
	v_add_f32_e32 v14, v14, v13
	v_fmac_f32_e32 v17, v12, v53
	v_add_f32_e32 v14, v14, v17
	v_fmac_f32_e32 v21, v12, v57
	v_add_f32_e32 v14, v14, v21
	v_fmac_f32_e32 v25, v12, v61
	v_add_f32_e32 v14, v14, v25
	v_fmac_f32_e32 v29, v12, v45
	v_add_f32_e32 v12, v14, v29
	ds_bpermute_b32 v14, v206, v12
	v_cvt_pk_bf16_f32 v18, v18, s0
	ds_write_b16 v10, v18 offset:64
	s_waitcnt lgkmcnt(1)
	v_add_f32_e32 v12, v12, v14
	ds_bpermute_b32 v14, v207, v12
	s_waitcnt lgkmcnt(0)
	v_add_f32_e32 v12, v12, v14
	ds_bpermute_b32 v14, v208, v12
	s_waitcnt lgkmcnt(0)
	v_add_f32_e32 v12, v12, v14
	ds_bpermute_b32 v14, v209, v12
	s_waitcnt lgkmcnt(0)
	v_add_f32_e32 v12, v12, v14
	v_fmac_f32_e32 v97, 0xbc000000, v12
	v_fmac_f32_e32 v90, 0xbc000000, v12
	v_mul_f32_e32 v14, v97, v97
	v_fmac_f32_e32 v14, v90, v90
	v_fmac_f32_e32 v98, 0xbc000000, v12
	v_fmac_f32_e32 v14, v98, v98
	v_fmac_f32_e32 v13, 0xbc000000, v12
	v_fmac_f32_e32 v14, v13, v13
	v_fmac_f32_e32 v17, 0xbc000000, v12
	v_fmac_f32_e32 v14, v17, v17
	v_fmac_f32_e32 v21, 0xbc000000, v12
	v_fmac_f32_e32 v14, v21, v21
	v_fmac_f32_e32 v25, 0xbc000000, v12
	v_fmac_f32_e32 v14, v25, v25
	v_fmac_f32_e32 v29, 0xbc000000, v12
	v_fmac_f32_e32 v14, v29, v29
	ds_bpermute_b32 v12, v206, v14
	s_waitcnt lgkmcnt(0)
	v_add_f32_e32 v12, v14, v12
	ds_bpermute_b32 v14, v207, v12
	s_waitcnt lgkmcnt(0)
	v_add_f32_e32 v12, v12, v14
	ds_bpermute_b32 v14, v208, v12
	s_waitcnt lgkmcnt(0)
	v_add_f32_e32 v12, v12, v14
	ds_bpermute_b32 v14, v209, v12
	s_waitcnt lgkmcnt(0)
	v_add_f32_e32 v12, v12, v14
	v_fmamk_f32 v12, v12, 0x3c000000, v217
	v_rsq_f32_e32 v12, v12
	s_nop 0
	v_mul_f32_e32 v13, v13, v12
	v_cvt_pk_bf16_f32 v13, v13, s0
	v_mul_f32_e32 v14, v90, v12
	ds_write_b16 v10, v13 offset:368
	v_mul_f32_e32 v13, v17, v12
	v_cvt_pk_bf16_f32 v14, v14, s0
	v_cvt_pk_bf16_f32 v13, v13, s0
	ds_write_b16 v10, v14 offset:272
	v_mul_f32_e32 v14, v97, v12
	ds_write_b16 v10, v13 offset:400
	v_mul_f32_e32 v13, v21, v12
	v_cvt_pk_bf16_f32 v14, v14, s0
	v_cvt_pk_bf16_f32 v13, v13, s0
	ds_write_b16 v10, v14 offset:304
	v_mul_f32_e32 v14, v98, v12
	ds_write_b16 v10, v13 offset:432
	v_mul_f32_e32 v13, v25, v12
	v_mul_f32_e32 v12, v29, v12
	v_cvt_pk_bf16_f32 v12, v12, s0
	ds_write_b16 v10, v12 offset:496
	v_sub_u32_e32 v12, 0x80, v102
	v_cvt_f32_i32_e32 v12, v12
	v_cvt_pk_bf16_f32 v13, v13, s0
	ds_write_b16 v10, v13 offset:464
	v_cvt_pk_bf16_f32 v14, v14, s0
	v_mul_f32_e32 v12, v12, v67
	v_mul_f32_e32 v12, 0xbfb8aa3b, v12
	v_exp_f32_e32 v12, v12
	ds_write_b16 v10, v14 offset:336
	v_fmac_f32_e32 v9, v12, v34
	v_add_f32_e32 v13, 0, v9
	v_fmac_f32_e32 v8, v12, v38
	v_add_f32_e32 v13, v13, v8
	v_fmac_f32_e32 v6, v12, v42
	v_add_f32_e32 v13, v13, v6
	v_fmac_f32_e32 v5, v12, v50
	v_add_f32_e32 v13, v13, v5
	v_fmac_f32_e32 v4, v12, v54
	v_add_f32_e32 v13, v13, v4
	v_fmac_f32_e32 v2, v12, v58
	v_add_f32_e32 v13, v13, v2
	v_fmac_f32_e32 v1, v12, v62
	v_add_f32_e32 v13, v13, v1
	v_fmac_f32_e32 v0, v12, v46
	v_add_f32_e32 v12, v13, v0
	ds_bpermute_b32 v13, v206, v12
	s_waitcnt lgkmcnt(0)
	v_add_f32_e32 v12, v12, v13
	ds_bpermute_b32 v13, v207, v12
	s_waitcnt lgkmcnt(0)
	v_add_f32_e32 v12, v12, v13
	ds_bpermute_b32 v13, v208, v12
	s_waitcnt lgkmcnt(0)
	v_add_f32_e32 v12, v12, v13
	ds_bpermute_b32 v13, v209, v12
	s_waitcnt lgkmcnt(0)
	v_add_f32_e32 v12, v12, v13
	v_fmac_f32_e32 v8, 0xbc000000, v12
	v_fmac_f32_e32 v9, 0xbc000000, v12
	v_mul_f32_e32 v13, v8, v8
	v_fmac_f32_e32 v13, v9, v9
	v_fmac_f32_e32 v6, 0xbc000000, v12
	v_fmac_f32_e32 v13, v6, v6
	v_fmac_f32_e32 v5, 0xbc000000, v12
	v_fmac_f32_e32 v13, v5, v5
	v_fmac_f32_e32 v4, 0xbc000000, v12
	v_fmac_f32_e32 v13, v4, v4
	v_fmac_f32_e32 v2, 0xbc000000, v12
	v_fmac_f32_e32 v13, v2, v2
	v_fmac_f32_e32 v1, 0xbc000000, v12
	v_fmac_f32_e32 v13, v1, v1
	v_fmac_f32_e32 v0, 0xbc000000, v12
	v_fmac_f32_e32 v13, v0, v0
	ds_bpermute_b32 v12, v206, v13
	s_waitcnt lgkmcnt(0)
	v_add_f32_e32 v12, v13, v12
	ds_bpermute_b32 v13, v207, v12
	s_waitcnt lgkmcnt(0)
	v_add_f32_e32 v12, v12, v13
	ds_bpermute_b32 v13, v208, v12
	s_waitcnt lgkmcnt(0)
	v_add_f32_e32 v12, v12, v13
	ds_bpermute_b32 v13, v209, v12
	s_waitcnt lgkmcnt(0)
; #define LAS __attribute__((address_space(3)))
; DI unsigned cvt_pk_bf16(float lo, float hi) { const f32x2 v = {lo, hi}; return __builtin_bit_cast(unsigned, __builtin_convertvector(v, bf16x2_t)); }
; DI float sigmoidf_(float x) { return __builtin_amdgcn_rcpf(1.f + __builtin_amdgcn_exp2f(-1.4426950408889634f * x)); }
; #define LDS_WAIT() asm volatile("s_waitcnt lgkmcnt(0)" ::: "memory")
; DI void unpack8(const u32x4 w, float (&f)[8]) { f[0] = bflo(w.x); f[1] = bfhi(w.x); f[2] = bflo(w.y); f[3] = bfhi(w.y); f[4] = bflo(w.z); f[5] = bfhi(w.z); f[6] = bflo(w.w); f[7] = bfhi(w.w); }
; DI void out_unit(const Inputs& in, int l, unsigned char* ws, int half, int u, LAS unsigned char* lds, int tid) {
;     ...
;     for (int r = 0; r < 4; ++r) { const int i = 16 * wave + 4 * quad + r; const float qwb = __expf((float)(128 - i) * lgb);
;         float sm = 0.f;
; #pragma unroll
;         for (int cg = 0; cg < 8; ++cg) { O[cg][r] += qwb * F[cg][r]; sm += O[cg][r]; }
;         sm += __shfl_xor(sm, 1); sm += __shfl_xor(sm, 2); sm += __shfl_xor(sm, 4); sm += __shfl_xor(sm, 8);
;         const float mean = sm * (1.f / 128.f); float vs = 0.f;
; #pragma unroll
;         for (int cg = 0; cg < 8; ++cg) { const float dd = O[cg][r] - mean; vs += dd * dd; }
;         vs += __shfl_xor(vs, 1); vs += __shfl_xor(vs, 2); vs += __shfl_xor(vs, 4); vs += __shfl_xor(vs, 8);
;         const float rinv = __builtin_amdgcn_rsqf(vs * (1.f / 128.f) + EPS);
; #pragma unroll
;         for (int cg = 0; cg < 8; ++cg) Pn[(4 * quad + r) * TS + 16 * cg + l15] = f2bf((O[cg][r] - mean) * rinv);
;     }
;     LDS_WAIT();
;     { const int rr = lane >> 2, part = lane & 3; bf16_t* rowp = proj + (size_t)(row0 + 16 * wave + rr) * PC + 128 * h + 32 * part;
;       u32x4 gv[4];
; #pragma unroll
;       for (int q = 0; q < 4; ++q) gv[q] = *(const u32x4*)(rowp + C_RG + 8 * q);
; #pragma unroll
;       for (int q = 0; q < 4; ++q) { float g[8], o[8]; unpack8(gv[q], g); unpack8(*(const LAS u32x4*)(Pn + rr * TS + 32 * part + 8 * q), o);
; #pragma unroll
;           for (int e = 0; e < 8; ++e) o[e] = g[e] * sigmoidf_(g[e]) * o[e];
;           u32x4 w; w.x = cvt_pk_bf16(o[0], o[1]); w.y = cvt_pk_bf16(o[2], o[3]); w.z = cvt_pk_bf16(o[4], o[5]); w.w = cvt_pk_bf16(o[6], o[7]);
;           *(u32x4*)(rowp + C_RQ + 8 * q) = w; } }
	v_add_f32_e32 v12, v12, v13
	v_fmamk_f32 v12, v12, 0x3c000000, v217
	v_rsq_f32_e32 v12, v12
	s_nop 0
	v_mul_f32_e32 v0, v0, v12
	v_cvt_pk_bf16_f32 v0, v0, s0
	ds_write_b16 v10, v0 offset:768
	v_sub_u32_e32 v0, 0x80, v100
	v_cvt_f32_i32_e32 v0, v0
	v_mul_f32_e32 v1, v1, v12
	v_cvt_pk_bf16_f32 v1, v1, s0
	ds_write_b16 v10, v1 offset:736
	v_mul_f32_e32 v0, v0, v67
	v_mul_f32_e32 v0, 0xbfb8aa3b, v0
	v_exp_f32_e32 v0, v0
	v_mul_f32_e32 v9, v9, v12
	v_mul_f32_e32 v8, v8, v12
	v_mul_f32_e32 v6, v6, v12
	v_fmac_f32_e32 v3, v0, v35
	v_add_f32_e32 v1, 0, v3
	v_fmac_f32_e32 v7, v0, v39
	v_add_f32_e32 v1, v1, v7
	v_fmac_f32_e32 v11, v0, v43
	v_add_f32_e32 v1, v1, v11
	v_fmac_f32_e32 v15, v0, v51
	v_add_f32_e32 v1, v1, v15
	v_fmac_f32_e32 v19, v0, v55
	v_add_f32_e32 v1, v1, v19
	v_fmac_f32_e32 v23, v0, v59
	v_add_f32_e32 v1, v1, v23
	v_fmac_f32_e32 v27, v0, v63
	v_add_f32_e32 v1, v1, v27
	v_fmac_f32_e32 v31, v0, v47
	v_add_f32_e32 v0, v1, v31
	ds_bpermute_b32 v1, v206, v0
	v_mul_f32_e32 v5, v5, v12
	v_mul_f32_e32 v4, v4, v12
	v_mul_f32_e32 v2, v2, v12
	v_cvt_pk_bf16_f32 v9, v9, s0
	s_waitcnt lgkmcnt(0)
	v_add_f32_e32 v0, v0, v1
	ds_bpermute_b32 v1, v207, v0
	v_cvt_pk_bf16_f32 v8, v8, s0
	v_cvt_pk_bf16_f32 v6, v6, s0
	v_cvt_pk_bf16_f32 v5, v5, s0
	v_cvt_pk_bf16_f32 v4, v4, s0
	s_waitcnt lgkmcnt(0)
	v_add_f32_e32 v0, v0, v1
	ds_bpermute_b32 v1, v208, v0
	v_cvt_pk_bf16_f32 v2, v2, s0
	ds_write_b16 v10, v9 offset:544
	ds_write_b16 v10, v8 offset:576
	ds_write_b16 v10, v6 offset:608
	s_waitcnt lgkmcnt(3)
	v_add_f32_e32 v0, v0, v1
	ds_bpermute_b32 v1, v209, v0
	ds_write_b16 v10, v5 offset:640
	ds_write_b16 v10, v4 offset:672
	ds_write_b16 v10, v2 offset:704
	v_lshlrev_b32_e32 v2, 6, v66
	s_waitcnt lgkmcnt(3)
	v_add_f32_e32 v0, v0, v1
	v_fmac_f32_e32 v7, 0xbc000000, v0
	v_fmac_f32_e32 v3, 0xbc000000, v0
	v_mul_f32_e32 v1, v7, v7
	v_fmac_f32_e32 v1, v3, v3
	v_fmac_f32_e32 v11, 0xbc000000, v0
	v_fmac_f32_e32 v1, v11, v11
	v_fmac_f32_e32 v15, 0xbc000000, v0
	v_fmac_f32_e32 v1, v15, v15
	v_fmac_f32_e32 v19, 0xbc000000, v0
	v_fmac_f32_e32 v1, v19, v19
	v_fmac_f32_e32 v23, 0xbc000000, v0
	v_fmac_f32_e32 v1, v23, v23
	v_fmac_f32_e32 v27, 0xbc000000, v0
	v_fmac_f32_e32 v1, v27, v27
	v_fmac_f32_e32 v31, 0xbc000000, v0
	v_fmac_f32_e32 v1, v31, v31
	ds_bpermute_b32 v0, v206, v1
	v_and_b32_e32 v176, 0xc0, v2
	s_waitcnt lgkmcnt(0)
	v_add_f32_e32 v0, v1, v0
	ds_bpermute_b32 v1, v207, v0
	s_waitcnt lgkmcnt(0)
	v_add_f32_e32 v0, v0, v1
	ds_bpermute_b32 v1, v208, v0
	s_waitcnt lgkmcnt(0)
	v_add_f32_e32 v0, v0, v1
	ds_bpermute_b32 v1, v209, v0
	s_waitcnt lgkmcnt(0)
	v_add_f32_e32 v0, v0, v1
	v_fmamk_f32 v0, v0, 0x3c000000, v217
	v_rsq_f32_e32 v0, v0
	s_nop 0
	v_mul_f32_e32 v1, v3, v0
	v_cvt_pk_bf16_f32 v1, v1, s0
	ds_write_b16 v10, v1 offset:816
	v_mul_f32_e32 v1, v7, v0
	v_cvt_pk_bf16_f32 v1, v1, s0
	ds_write_b16 v10, v1 offset:848
	v_mul_f32_e32 v1, v11, v0
	v_cvt_pk_bf16_f32 v1, v1, s0
	ds_write_b16 v10, v1 offset:880
	v_mul_f32_e32 v1, v15, v0
	v_cvt_pk_bf16_f32 v1, v1, s0
	ds_write_b16 v10, v1 offset:912
	v_mul_f32_e32 v1, v19, v0
	v_cvt_pk_bf16_f32 v1, v1, s0
	ds_write_b16 v10, v1 offset:944
	v_mul_f32_e32 v1, v23, v0
	v_cvt_pk_bf16_f32 v1, v1, s0
	ds_write_b16 v10, v1 offset:976
	v_mul_f32_e32 v1, v27, v0
	v_mul_f32_e32 v0, v31, v0
	v_cvt_pk_bf16_f32 v1, v1, s0
	v_cvt_pk_bf16_f32 v0, v0, s0
	ds_write_b16 v10, v1 offset:1008
	ds_write_b16 v10, v0 offset:1040
	v_bfe_u32 v10, v66, 2, 4
	v_add_u32_e32 v0, s14, v69
	v_or_b32_e32 v0, v0, v10
	v_ashrrev_i32_e32 v1, 31, v0
	v_lshlrev_b64 v[0:1], 14, v[0:1]
	v_lshl_add_u64 v[0:1], s[6:7], 0, v[0:1]
	v_lshl_add_u64 v[0:1], v[0:1], 0, s[44:45]
	v_lshl_add_u64 v[8:9], v[0:1], 0, v[176:177]
	s_mov_b64 s[14:15], 0x1800
	v_add_co_u32_e32 v0, vcc, s30, v8
	s_waitcnt lgkmcnt(0)
	v_lshl_add_u64 v[16:17], v[8:9], 0, s[14:15]
	s_nop 0
	v_addc_co_u32_e32 v1, vcc, 0, v9, vcc
	global_load_dwordx4 v[12:15], v[0:1], off offset:2048
	s_nop 0
	global_load_dwordx4 v[0:3], v[16:17], off offset:48
	global_load_dwordx4 v[4:7], v[16:17], off offset:32
	s_nop 0
	global_load_dwordx4 v[16:19], v[16:17], off offset:16
	v_mul_u32_u24_e32 v10, 0x110, v10
	v_add3_u32 v10, v65, v10, v176
	ds_read_b128 v[20:23], v10
	ds_read_b128 v[24:27], v10 offset:16
	ds_read_b128 v[28:31], v10 offset:32
	ds_read_b128 v[32:35], v10 offset:48
	s_waitcnt lgkmcnt(3)
	v_lshlrev_b32_e32 v36, 16, v20
	v_and_b32_e32 v37, 0xffff0000, v20
	v_lshlrev_b32_e32 v20, 16, v21
	v_and_b32_e32 v21, 0xffff0000, v21
	s_waitcnt vmcnt(3)
	v_lshlrev_b32_e32 v10, 16, v12
	v_and_b32_e32 v11, 0xffff0000, v12
	v_mul_f32_e32 v12, 0xbfb8aa3b, v10
	v_exp_f32_e32 v12, v12
	s_nop 0
	v_add_f32_e32 v12, 1.0, v12
	v_rcp_f32_e32 v38, v12
	v_mul_f32_e32 v12, 0xbfb8aa3b, v11
	v_exp_f32_e32 v12, v12
	s_nop 0
	v_add_f32_e32 v12, 1.0, v12
	v_rcp_f32_e32 v39, v12
	v_lshlrev_b32_e32 v12, 16, v13
	v_and_b32_e32 v13, 0xffff0000, v13
	v_pk_mul_f32 v[10:11], v[38:39], v[10:11]
	s_nop 0
	v_pk_mul_f32 v[10:11], v[10:11], v[36:37]
	v_mul_f32_e32 v36, 0xbfb8aa3b, v12
	v_mul_f32_e32 v37, 0xbfb8aa3b, v13
	v_exp_f32_e32 v36, v36
	v_exp_f32_e32 v37, v37
	v_cvt_pk_bf16_f32 v10, v10, v11
	v_add_f32_e32 v36, 1.0, v36
	v_add_f32_e32 v37, 1.0, v37
	v_rcp_f32_e32 v36, v36
	v_rcp_f32_e32 v37, v37
	s_nop 0
	v_pk_mul_f32 v[12:13], v[36:37], v[12:13]
	s_nop 0
	v_pk_mul_f32 v[12:13], v[12:13], v[20:21]
	v_lshlrev_b32_e32 v20, 16, v14
	v_and_b32_e32 v21, 0xffff0000, v14
	v_mul_f32_e32 v14, 0xbfb8aa3b, v20
	v_exp_f32_e32 v14, v14
	v_lshlrev_b32_e32 v36, 16, v22
	v_and_b32_e32 v37, 0xffff0000, v22
	v_lshlrev_b32_e32 v22, 16, v23
	v_add_f32_e32 v14, 1.0, v14
	v_rcp_f32_e32 v38, v14
	v_mul_f32_e32 v14, 0xbfb8aa3b, v21
	v_exp_f32_e32 v14, v14
	v_and_b32_e32 v23, 0xffff0000, v23
	v_cvt_pk_bf16_f32 v11, v12, v13
	v_add_f32_e32 v14, 1.0, v14
	v_rcp_f32_e32 v39, v14
	v_lshlrev_b32_e32 v14, 16, v15
	v_and_b32_e32 v15, 0xffff0000, v15
	v_pk_mul_f32 v[20:21], v[38:39], v[20:21]
	s_nop 0
	v_pk_mul_f32 v[20:21], v[20:21], v[36:37]
	v_mul_f32_e32 v36, 0xbfb8aa3b, v14
	v_mul_f32_e32 v37, 0xbfb8aa3b, v15
	v_exp_f32_e32 v36, v36
	v_exp_f32_e32 v37, v37
	v_cvt_pk_bf16_f32 v12, v20, v21
	v_add_f32_e32 v36, 1.0, v36
	v_add_f32_e32 v37, 1.0, v37
	v_rcp_f32_e32 v36, v36
	v_rcp_f32_e32 v37, v37
	s_nop 0
	v_pk_mul_f32 v[14:15], v[36:37], v[14:15]
	s_nop 0
	v_pk_mul_f32 v[14:15], v[14:15], v[22:23]
	s_nop 0
	v_cvt_pk_bf16_f32 v13, v14, v15
	global_store_dwordx4 v[8:9], v[10:13], off offset:3072
	s_waitcnt vmcnt(1)
; #define LAS __attribute__((address_space(3)))
; DI unsigned cvt_pk_bf16(float lo, float hi) { const f32x2 v = {lo, hi}; return __builtin_bit_cast(unsigned, __builtin_convertvector(v, bf16x2_t)); }
; DI float sigmoidf_(float x) { return __builtin_amdgcn_rcpf(1.f + __builtin_amdgcn_exp2f(-1.4426950408889634f * x)); }
; DI void unpack8(const u32x4 w, float (&f)[8]) { f[0] = bflo(w.x); f[1] = bfhi(w.x); f[2] = bflo(w.y); f[3] = bfhi(w.y); f[4] = bflo(w.z); f[5] = bfhi(w.z); f[6] = bflo(w.w); f[7] = bfhi(w.w); }
; DI void out_unit(const Inputs& in, int l, unsigned char* ws, int half, int u, LAS unsigned char* lds, int tid) {
;     ...
;       for (int q = 0; q < 4; ++q) gv[q] = *(const u32x4*)(rowp + C_RG + 8 * q);
; #pragma unroll
;       for (int q = 0; q < 4; ++q) { float g[8], o[8]; unpack8(gv[q], g); unpack8(*(const LAS u32x4*)(Pn + rr * TS + 32 * part + 8 * q), o);
; #pragma unroll
;           for (int e = 0; e < 8; ++e) o[e] = g[e] * sigmoidf_(g[e]) * o[e];
;           u32x4 w; w.x = cvt_pk_bf16(o[0], o[1]); w.y = cvt_pk_bf16(o[2], o[3]); w.z = cvt_pk_bf16(o[4], o[5]); w.w = cvt_pk_bf16(o[6], o[7]);
;           *(u32x4*)(rowp + C_RQ + 8 * q) = w; } }
;     __syncthreads();
	s_nop 0
	v_lshlrev_b32_e32 v10, 16, v16
	v_and_b32_e32 v11, 0xffff0000, v16
	v_mul_f32_e32 v14, 0xbfb8aa3b, v10
	v_mul_f32_e32 v15, 0xbfb8aa3b, v11
	v_exp_f32_e32 v14, v14
	v_exp_f32_e32 v15, v15
	s_waitcnt lgkmcnt(2)
	v_lshlrev_b32_e32 v12, 16, v24
	v_and_b32_e32 v13, 0xffff0000, v24
	v_add_f32_e32 v14, 1.0, v14
	v_add_f32_e32 v15, 1.0, v15
	v_rcp_f32_e32 v14, v14
	v_rcp_f32_e32 v15, v15
	s_nop 0
	v_pk_mul_f32 v[10:11], v[14:15], v[10:11]
	s_nop 0
	v_pk_mul_f32 v[10:11], v[10:11], v[12:13]
	v_lshlrev_b32_e32 v12, 16, v17
	v_and_b32_e32 v13, 0xffff0000, v17
	v_mul_f32_e32 v16, 0xbfb8aa3b, v12
	v_mul_f32_e32 v17, 0xbfb8aa3b, v13
	v_exp_f32_e32 v16, v16
	v_exp_f32_e32 v17, v17
	v_lshlrev_b32_e32 v14, 16, v25
	v_and_b32_e32 v15, 0xffff0000, v25
	v_add_f32_e32 v16, 1.0, v16
	v_add_f32_e32 v17, 1.0, v17
	v_rcp_f32_e32 v16, v16
	v_rcp_f32_e32 v17, v17
	v_cvt_pk_bf16_f32 v10, v10, v11
	v_pk_mul_f32 v[12:13], v[16:17], v[12:13]
	s_nop 0
	v_pk_mul_f32 v[12:13], v[12:13], v[14:15]
	v_lshlrev_b32_e32 v14, 16, v18
	v_and_b32_e32 v15, 0xffff0000, v18
	v_mul_f32_e32 v18, 0xbfb8aa3b, v14
	v_exp_f32_e32 v18, v18
	v_lshlrev_b32_e32 v16, 16, v26
	v_and_b32_e32 v17, 0xffff0000, v26
	v_cvt_pk_bf16_f32 v11, v12, v13
	v_add_f32_e32 v18, 1.0, v18
	v_rcp_f32_e32 v20, v18
	v_mul_f32_e32 v18, 0xbfb8aa3b, v15
	v_exp_f32_e32 v18, v18
	s_nop 0
	v_add_f32_e32 v18, 1.0, v18
	v_rcp_f32_e32 v21, v18
	v_lshlrev_b32_e32 v18, 16, v27
	v_pk_mul_f32 v[14:15], v[20:21], v[14:15]
	s_nop 0
	v_pk_mul_f32 v[14:15], v[14:15], v[16:17]
	v_lshlrev_b32_e32 v16, 16, v19
	v_and_b32_e32 v17, 0xffff0000, v19
	v_mul_f32_e32 v20, 0xbfb8aa3b, v16
	v_mul_f32_e32 v21, 0xbfb8aa3b, v17
	v_exp_f32_e32 v20, v20
	v_exp_f32_e32 v21, v21
	v_and_b32_e32 v19, 0xffff0000, v27
	v_cvt_pk_bf16_f32 v12, v14, v15
	v_add_f32_e32 v20, 1.0, v20
	v_add_f32_e32 v21, 1.0, v21
	v_rcp_f32_e32 v20, v20
	v_rcp_f32_e32 v21, v21
	s_nop 0
	v_pk_mul_f32 v[16:17], v[20:21], v[16:17]
	s_nop 0
	v_pk_mul_f32 v[16:17], v[16:17], v[18:19]
	s_nop 0
	v_cvt_pk_bf16_f32 v13, v16, v17
	global_store_dwordx4 v[8:9], v[10:13], off offset:3088
	s_nop 1
	v_lshlrev_b32_e32 v10, 16, v4
	v_and_b32_e32 v11, 0xffff0000, v4
	v_mul_f32_e32 v4, 0xbfb8aa3b, v10
	v_exp_f32_e32 v4, v4
	s_waitcnt lgkmcnt(1)
	v_lshlrev_b32_e32 v12, 16, v28
	v_and_b32_e32 v13, 0xffff0000, v28
	v_add_f32_e32 v4, 1.0, v4
	v_rcp_f32_e32 v14, v4
	v_mul_f32_e32 v4, 0xbfb8aa3b, v11
	v_exp_f32_e32 v4, v4
	s_nop 0
	v_add_f32_e32 v4, 1.0, v4
	v_rcp_f32_e32 v15, v4
	v_lshlrev_b32_e32 v4, 16, v5
	v_and_b32_e32 v5, 0xffff0000, v5
	v_pk_mul_f32 v[10:11], v[14:15], v[10:11]
	v_mul_f32_e32 v14, 0xbfb8aa3b, v4
	v_mul_f32_e32 v15, 0xbfb8aa3b, v5
	v_exp_f32_e32 v14, v14
	v_exp_f32_e32 v15, v15
	v_pk_mul_f32 v[10:11], v[10:11], v[12:13]
	v_lshlrev_b32_e32 v12, 16, v29
	v_add_f32_e32 v14, 1.0, v14
	v_add_f32_e32 v15, 1.0, v15
	v_rcp_f32_e32 v14, v14
	v_rcp_f32_e32 v15, v15
	v_and_b32_e32 v13, 0xffff0000, v29
	v_pk_mul_f32 v[4:5], v[14:15], v[4:5]
	s_nop 0
	v_pk_mul_f32 v[12:13], v[4:5], v[12:13]
	v_lshlrev_b32_e32 v4, 16, v6
	v_and_b32_e32 v5, 0xffff0000, v6
	v_mul_f32_e32 v6, 0xbfb8aa3b, v4
	v_exp_f32_e32 v6, v6
	v_lshlrev_b32_e32 v14, 16, v30
	v_and_b32_e32 v15, 0xffff0000, v30
	v_add_f32_e32 v6, 1.0, v6
	v_rcp_f32_e32 v16, v6
	v_mul_f32_e32 v6, 0xbfb8aa3b, v5
	v_exp_f32_e32 v6, v6
	s_nop 0
	v_add_f32_e32 v6, 1.0, v6
	v_rcp_f32_e32 v17, v6
	v_lshlrev_b32_e32 v6, 16, v31
	v_pk_mul_f32 v[4:5], v[16:17], v[4:5]
	s_nop 0
	v_pk_mul_f32 v[14:15], v[4:5], v[14:15]
	v_lshlrev_b32_e32 v4, 16, v7
	v_and_b32_e32 v5, 0xffff0000, v7
	v_mul_f32_e32 v16, 0xbfb8aa3b, v4
	v_mul_f32_e32 v17, 0xbfb8aa3b, v5
	v_exp_f32_e32 v16, v16
	v_exp_f32_e32 v17, v17
	v_and_b32_e32 v7, 0xffff0000, v31
	v_add_f32_e32 v16, 1.0, v16
	v_add_f32_e32 v17, 1.0, v17
	v_rcp_f32_e32 v16, v16
	v_rcp_f32_e32 v17, v17
	s_nop 0
	v_pk_mul_f32 v[4:5], v[16:17], v[4:5]
	s_nop 0
	v_pk_mul_f32 v[16:17], v[4:5], v[6:7]
	v_cvt_pk_bf16_f32 v4, v10, v11
	v_cvt_pk_bf16_f32 v5, v12, v13
	v_cvt_pk_bf16_f32 v6, v14, v15
	v_cvt_pk_bf16_f32 v7, v16, v17
	global_store_dwordx4 v[8:9], v[4:7], off offset:3104
	s_nop 1
	v_lshlrev_b32_e32 v4, 16, v0
	v_and_b32_e32 v5, 0xffff0000, v0
	v_mul_f32_e32 v0, 0xbfb8aa3b, v4
	v_exp_f32_e32 v0, v0
	s_waitcnt lgkmcnt(0)
	v_lshlrev_b32_e32 v6, 16, v32
	v_and_b32_e32 v7, 0xffff0000, v32
	v_add_f32_e32 v0, 1.0, v0
	v_rcp_f32_e32 v10, v0
	v_mul_f32_e32 v0, 0xbfb8aa3b, v5
	v_exp_f32_e32 v0, v0
	s_nop 0
	v_add_f32_e32 v0, 1.0, v0
	v_rcp_f32_e32 v11, v0
	v_lshlrev_b32_e32 v0, 16, v1
	v_and_b32_e32 v1, 0xffff0000, v1
	v_pk_mul_f32 v[4:5], v[10:11], v[4:5]
	v_mul_f32_e32 v10, 0xbfb8aa3b, v0
	v_mul_f32_e32 v11, 0xbfb8aa3b, v1
	v_exp_f32_e32 v10, v10
	v_exp_f32_e32 v11, v11
	v_pk_mul_f32 v[4:5], v[4:5], v[6:7]
	v_lshlrev_b32_e32 v6, 16, v33
	v_add_f32_e32 v10, 1.0, v10
	v_add_f32_e32 v11, 1.0, v11
	v_rcp_f32_e32 v10, v10
	v_rcp_f32_e32 v11, v11
	v_and_b32_e32 v7, 0xffff0000, v33
	v_pk_mul_f32 v[0:1], v[10:11], v[0:1]
	s_nop 0
	v_pk_mul_f32 v[6:7], v[0:1], v[6:7]
	v_lshlrev_b32_e32 v0, 16, v2
	v_and_b32_e32 v1, 0xffff0000, v2
	v_mul_f32_e32 v2, 0xbfb8aa3b, v0
	v_exp_f32_e32 v2, v2
	v_lshlrev_b32_e32 v10, 16, v34
	v_and_b32_e32 v11, 0xffff0000, v34
	v_add_f32_e32 v2, 1.0, v2
	v_rcp_f32_e32 v12, v2
	v_mul_f32_e32 v2, 0xbfb8aa3b, v1
	v_exp_f32_e32 v2, v2
	s_nop 0
	v_add_f32_e32 v2, 1.0, v2
	v_rcp_f32_e32 v13, v2
	v_lshlrev_b32_e32 v2, 16, v35
	v_pk_mul_f32 v[0:1], v[12:13], v[0:1]
	s_nop 0
	v_pk_mul_f32 v[10:11], v[0:1], v[10:11]
	v_lshlrev_b32_e32 v0, 16, v3
	v_and_b32_e32 v1, 0xffff0000, v3
	v_mul_f32_e32 v12, 0xbfb8aa3b, v0
	v_mul_f32_e32 v13, 0xbfb8aa3b, v1
	v_exp_f32_e32 v12, v12
	v_exp_f32_e32 v13, v13
	v_and_b32_e32 v3, 0xffff0000, v35
	v_add_f32_e32 v12, 1.0, v12
	v_add_f32_e32 v13, 1.0, v13
	v_rcp_f32_e32 v12, v12
	v_rcp_f32_e32 v13, v13
	s_nop 0
	v_pk_mul_f32 v[0:1], v[12:13], v[0:1]
	s_nop 0
	v_pk_mul_f32 v[12:13], v[0:1], v[2:3]
	v_cvt_pk_bf16_f32 v0, v4, v5
	v_cvt_pk_bf16_f32 v1, v6, v7
	v_cvt_pk_bf16_f32 v2, v10, v11
	v_cvt_pk_bf16_f32 v3, v12, v13
	global_store_dwordx4 v[8:9], v[0:3], off offset:3120
	s_barrier
	s_cbranch_scc0 .LBB0_731
